# weight-conversion (transpose_item) load loops de-serialized in P0 and P2b: all 32 row loads (+32 gain loads) of an item in flight instead of one dependent round trip per row
# speedup vs baseline: 1.1235x; 1.0599x over previous
;     ...
;     for (int i = 0; i < 32; ++i) { const int kk = 2 * i + (lane >> 5); float v = W[(size_t)(k0 + kk) * ldw + n0src + (lane & 31)]; if (gain) v *= gain[k0 + kk]; scr[kk * 33 + (lane & 31)] = v; }
; __device__ __forceinline__ void convert_weights(const Params& P, LAS unsigned char* lds, int gw, int NGW, int it0, int it1) {
;     ...
;         if (r < I_IN) { const int kb = r / 264, nb = r % 264, n0 = nb * 32; transpose_item(P.in[12], 8456, kb * 64, n0 + (n0 >= 6400 ? 8 : 0), (bf16*)(ws + WS_WIN), DM, n0, P.in[11], scr, lane); continue; } r -= I_IN;
.LBB0_84:
	v_lshl_add_u64 v[42:43], v[10:11], 0, s[10:11]
	global_load_dword v64, v[42:43], off
	v_lshl_add_u64 v[42:43], v[24:25], 0, s[10:11]
	global_load_dword v65, v[42:43], off
	v_lshl_add_u64 v[42:43], v[22:23], 0, s[10:11]
	global_load_dword v66, v[42:43], off
	v_lshl_add_u64 v[42:43], v[20:21], 0, s[10:11]
	global_load_dword v67, v[42:43], off
	v_lshl_add_u64 v[42:43], v[18:19], 0, s[10:11]
	global_load_dword v68, v[42:43], off
	v_lshl_add_u64 v[42:43], v[16:17], 0, s[10:11]
	global_load_dword v69, v[42:43], off
	v_lshl_add_u64 v[42:43], v[12:13], 0, s[10:11]
	global_load_dword v70, v[42:43], off
	v_lshl_add_u64 v[42:43], v[8:9], 0, s[10:11]
	global_load_dword v71, v[42:43], off
	s_add_u32 s10, s10, 0x84200
	s_addc_u32 s11, s11, 0
	v_lshl_add_u64 v[42:43], v[10:11], 0, s[10:11]
	global_load_dword v72, v[42:43], off
	v_lshl_add_u64 v[42:43], v[24:25], 0, s[10:11]
	global_load_dword v73, v[42:43], off
	v_lshl_add_u64 v[42:43], v[22:23], 0, s[10:11]
	global_load_dword v74, v[42:43], off
	v_lshl_add_u64 v[42:43], v[20:21], 0, s[10:11]
	global_load_dword v75, v[42:43], off
	v_lshl_add_u64 v[42:43], v[18:19], 0, s[10:11]
	global_load_dword v76, v[42:43], off
	v_lshl_add_u64 v[42:43], v[16:17], 0, s[10:11]
	global_load_dword v77, v[42:43], off
	v_lshl_add_u64 v[42:43], v[12:13], 0, s[10:11]
	global_load_dword v78, v[42:43], off
	v_lshl_add_u64 v[42:43], v[8:9], 0, s[10:11]
	global_load_dword v79, v[42:43], off
	s_add_u32 s10, s10, 0x84200
	s_addc_u32 s11, s11, 0
	v_lshl_add_u64 v[42:43], v[10:11], 0, s[10:11]
	global_load_dword v80, v[42:43], off
	v_lshl_add_u64 v[42:43], v[24:25], 0, s[10:11]
	global_load_dword v81, v[42:43], off
	v_lshl_add_u64 v[42:43], v[22:23], 0, s[10:11]
	global_load_dword v82, v[42:43], off
	v_lshl_add_u64 v[42:43], v[20:21], 0, s[10:11]
	global_load_dword v83, v[42:43], off
	v_lshl_add_u64 v[42:43], v[18:19], 0, s[10:11]
	global_load_dword v84, v[42:43], off
	v_lshl_add_u64 v[42:43], v[16:17], 0, s[10:11]
	global_load_dword v85, v[42:43], off
	v_lshl_add_u64 v[42:43], v[12:13], 0, s[10:11]
	global_load_dword v86, v[42:43], off
	v_lshl_add_u64 v[42:43], v[8:9], 0, s[10:11]
	global_load_dword v87, v[42:43], off
	s_add_u32 s10, s10, 0x84200
	s_addc_u32 s11, s11, 0
	v_lshl_add_u64 v[42:43], v[10:11], 0, s[10:11]
	global_load_dword v88, v[42:43], off
	v_lshl_add_u64 v[42:43], v[24:25], 0, s[10:11]
	global_load_dword v89, v[42:43], off
	v_lshl_add_u64 v[42:43], v[22:23], 0, s[10:11]
	global_load_dword v90, v[42:43], off
	v_lshl_add_u64 v[42:43], v[20:21], 0, s[10:11]
	global_load_dword v91, v[42:43], off
	v_lshl_add_u64 v[42:43], v[18:19], 0, s[10:11]
	global_load_dword v92, v[42:43], off
	v_lshl_add_u64 v[42:43], v[16:17], 0, s[10:11]
	global_load_dword v93, v[42:43], off
	v_lshl_add_u64 v[42:43], v[12:13], 0, s[10:11]
	global_load_dword v94, v[42:43], off
	v_lshl_add_u64 v[42:43], v[8:9], 0, s[10:11]
	global_load_dword v95, v[42:43], off
	s_andn2_b64 vcc, exec, s[54:55]
	s_cbranch_vccnz .Lcw0_nogain
	global_load_dword v96, v[14:15], off offset:-56
	global_load_dword v97, v[14:15], off offset:-48
	global_load_dword v98, v[14:15], off offset:-40
	global_load_dword v99, v[14:15], off offset:-32
	global_load_dword v100, v[14:15], off offset:-24
	global_load_dword v101, v[14:15], off offset:-16
	global_load_dword v102, v[14:15], off offset:-8
	global_load_dword v103, v[14:15], off offset:0
	global_load_dword v104, v[14:15], off offset:8
	global_load_dword v105, v[14:15], off offset:16
	global_load_dword v106, v[14:15], off offset:24
	global_load_dword v107, v[14:15], off offset:32
	global_load_dword v108, v[14:15], off offset:40
	global_load_dword v109, v[14:15], off offset:48
	global_load_dword v110, v[14:15], off offset:56
	global_load_dword v111, v[14:15], off offset:64
	global_load_dword v112, v[14:15], off offset:72
	global_load_dword v113, v[14:15], off offset:80
	global_load_dword v114, v[14:15], off offset:88
	global_load_dword v115, v[14:15], off offset:96
	global_load_dword v116, v[14:15], off offset:104
	global_load_dword v117, v[14:15], off offset:112
	global_load_dword v118, v[14:15], off offset:120
	global_load_dword v119, v[14:15], off offset:128
	global_load_dword v120, v[14:15], off offset:136
	global_load_dword v121, v[14:15], off offset:144
	global_load_dword v122, v[14:15], off offset:152
	global_load_dword v123, v[14:15], off offset:160
	global_load_dword v124, v[14:15], off offset:168
	global_load_dword v125, v[14:15], off offset:176
	global_load_dword v126, v[14:15], off offset:184
	global_load_dword v127, v[14:15], off offset:192
	s_waitcnt vmcnt(0)
	v_mul_f32_e32 v64, v64, v96
	v_mul_f32_e32 v65, v65, v97
	v_mul_f32_e32 v66, v66, v98
	v_mul_f32_e32 v67, v67, v99
	v_mul_f32_e32 v68, v68, v100
	v_mul_f32_e32 v69, v69, v101
	v_mul_f32_e32 v70, v70, v102
	v_mul_f32_e32 v71, v71, v103
	v_mul_f32_e32 v72, v72, v104
	v_mul_f32_e32 v73, v73, v105
	v_mul_f32_e32 v74, v74, v106
	v_mul_f32_e32 v75, v75, v107
	v_mul_f32_e32 v76, v76, v108
	v_mul_f32_e32 v77, v77, v109
	v_mul_f32_e32 v78, v78, v110
	v_mul_f32_e32 v79, v79, v111
	v_mul_f32_e32 v80, v80, v112
	v_mul_f32_e32 v81, v81, v113
	v_mul_f32_e32 v82, v82, v114
	v_mul_f32_e32 v83, v83, v115
	v_mul_f32_e32 v84, v84, v116
	v_mul_f32_e32 v85, v85, v117
	v_mul_f32_e32 v86, v86, v118
	v_mul_f32_e32 v87, v87, v119
	v_mul_f32_e32 v88, v88, v120
	v_mul_f32_e32 v89, v89, v121
	v_mul_f32_e32 v90, v90, v122
	v_mul_f32_e32 v91, v91, v123
	v_mul_f32_e32 v92, v92, v124
	v_mul_f32_e32 v93, v93, v125
	v_mul_f32_e32 v94, v94, v126
	v_mul_f32_e32 v95, v95, v127
.Lcw0_nogain:
	s_waitcnt vmcnt(0)
	ds_write_b32 v39, v64 offset:0
	ds_write_b32 v39, v65 offset:264
	ds_write_b32 v39, v66 offset:528
	ds_write_b32 v39, v67 offset:792
	ds_write_b32 v39, v68 offset:1056
	ds_write_b32 v39, v69 offset:1320
	ds_write_b32 v39, v70 offset:1584
	ds_write_b32 v39, v71 offset:1848
	ds_write_b32 v39, v72 offset:2112
	ds_write_b32 v39, v73 offset:2376
	ds_write_b32 v39, v74 offset:2640
	ds_write_b32 v39, v75 offset:2904
	ds_write_b32 v39, v76 offset:3168
	ds_write_b32 v39, v77 offset:3432
	ds_write_b32 v39, v78 offset:3696
	ds_write_b32 v39, v79 offset:3960
	ds_write_b32 v39, v80 offset:4224
	ds_write_b32 v39, v81 offset:4488
	ds_write_b32 v39, v82 offset:4752
	ds_write_b32 v39, v83 offset:5016
	ds_write_b32 v39, v84 offset:5280
	ds_write_b32 v39, v85 offset:5544
	ds_write_b32 v39, v86 offset:5808
	ds_write_b32 v39, v87 offset:6072
	ds_write_b32 v39, v88 offset:6336
	ds_write_b32 v39, v89 offset:6600
	ds_write_b32 v39, v90 offset:6864
	ds_write_b32 v39, v91 offset:7128
	ds_write_b32 v39, v92 offset:7392
	ds_write_b32 v39, v93 offset:7656
	ds_write_b32 v39, v94 offset:7920
	ds_write_b32 v39, v95 offset:8184
	s_branch .LBB0_81

;     ...
;     for (int i = 0; i < 32; ++i) { const int kk = 2 * i + (lane >> 5); float v = W[(size_t)(k0 + kk) * ldw + n0src + (lane & 31)]; if (gain) v *= gain[k0 + kk]; scr[kk * 33 + (lane & 31)] = v; }
; __device__ __forceinline__ void convert_weights(const Params& P, LAS unsigned char* lds, int gw, int NGW, int it0, int it1) {
;     ...
;         { const int kb = r / 32, nb = r % 32; transpose_item(P.in[27], DM, kb * 64, nb * 32, (bf16*)(ws + WS_WPP), 256, nb * 32, nullptr, scr, lane); }
.LBB0_587:
	s_lshl_b32 s52, s15, 1
	s_lshl_b32 s19, s14, 1
	v_or_b32_e32 v54, s52, v0
	v_or_b32_e32 v47, s19, v1
	v_add_u32_e32 v52, v54, v46
	v_add_u32_e32 v50, v47, v3
	v_ashrrev_i32_e32 v53, 31, v52
	v_ashrrev_i32_e32 v51, 31, v50
	v_lshlrev_b64 v[52:53], 12, v[52:53]
	v_lshlrev_b64 v[50:51], 12, v[50:51]
	v_lshl_add_u64 v[52:53], v[48:49], 0, v[52:53]
	v_lshl_add_u64 v[50:51], v[48:49], 0, v[50:51]
	global_load_dword v96, v[52:53], off
	global_load_dword v97, v[50:51], off
	v_mad_u64_u32 v[98:99], s[34:35], v54, s30, v[2:3]
	v_mad_u64_u32 v[100:101], s[34:35], v47, s30, v[2:3]
	s_add_i32 s35, s52, 4
	s_add_i32 s34, s19, 4
	v_or_b32_e32 v54, s35, v0
	v_or_b32_e32 v47, s34, v1
	s_add_i32 s15, s15, 16
	s_add_i32 s14, s14, 16
	s_add_i32 s18, s18, -16
	v_add_u32_e32 v52, v54, v46
	v_add_u32_e32 v50, v47, v3
	v_ashrrev_i32_e32 v53, 31, v52
	v_ashrrev_i32_e32 v51, 31, v50
	v_lshlrev_b64 v[52:53], 12, v[52:53]
	v_lshlrev_b64 v[50:51], 12, v[50:51]
	v_lshl_add_u64 v[52:53], v[48:49], 0, v[52:53]
	v_lshl_add_u64 v[50:51], v[48:49], 0, v[50:51]
	global_load_dword v102, v[52:53], off
	global_load_dword v103, v[50:51], off
	v_mad_u64_u32 v[104:105], s[34:35], v54, s30, v[2:3]
	v_mad_u64_u32 v[106:107], s[34:35], v47, s30, v[2:3]
	s_add_i32 s35, s52, 8
	s_add_i32 s34, s19, 8
	v_or_b32_e32 v54, s35, v0
	v_or_b32_e32 v47, s34, v1
	v_add_u32_e32 v52, v54, v46
	v_add_u32_e32 v50, v47, v3
	v_ashrrev_i32_e32 v53, 31, v52
	v_ashrrev_i32_e32 v51, 31, v50
	v_lshlrev_b64 v[52:53], 12, v[52:53]
	v_lshlrev_b64 v[50:51], 12, v[50:51]
	v_lshl_add_u64 v[52:53], v[48:49], 0, v[52:53]
	v_lshl_add_u64 v[50:51], v[48:49], 0, v[50:51]
	global_load_dword v108, v[52:53], off
	global_load_dword v109, v[50:51], off
	v_mad_u64_u32 v[110:111], s[34:35], v54, s30, v[2:3]
	v_mad_u64_u32 v[112:113], s[34:35], v47, s30, v[2:3]
	s_add_i32 s35, s52, 12
	s_add_i32 s34, s19, 12
	v_or_b32_e32 v54, s35, v0
	v_or_b32_e32 v47, s34, v1
	v_add_u32_e32 v52, v54, v46
	v_add_u32_e32 v50, v47, v3
	v_ashrrev_i32_e32 v53, 31, v52
	v_ashrrev_i32_e32 v51, 31, v50
	v_lshlrev_b64 v[52:53], 12, v[52:53]
	v_lshlrev_b64 v[50:51], 12, v[50:51]
	v_lshl_add_u64 v[52:53], v[48:49], 0, v[52:53]
	v_lshl_add_u64 v[50:51], v[48:49], 0, v[50:51]
	global_load_dword v114, v[52:53], off
	global_load_dword v115, v[50:51], off
	v_mad_u64_u32 v[116:117], s[34:35], v54, s30, v[2:3]
	v_mad_u64_u32 v[118:119], s[34:35], v47, s30, v[2:3]
	s_add_i32 s35, s52, 16
	s_add_i32 s34, s19, 16
	v_or_b32_e32 v54, s35, v0
	v_or_b32_e32 v47, s34, v1
	v_add_u32_e32 v52, v54, v46
	v_add_u32_e32 v50, v47, v3
	v_ashrrev_i32_e32 v53, 31, v52
	v_ashrrev_i32_e32 v51, 31, v50
	v_lshlrev_b64 v[52:53], 12, v[52:53]
	v_lshlrev_b64 v[50:51], 12, v[50:51]
	v_lshl_add_u64 v[52:53], v[48:49], 0, v[52:53]
	v_lshl_add_u64 v[50:51], v[48:49], 0, v[50:51]
	global_load_dword v120, v[52:53], off
	global_load_dword v121, v[50:51], off
	v_mad_u64_u32 v[122:123], s[34:35], v54, s30, v[2:3]
	v_mad_u64_u32 v[124:125], s[34:35], v47, s30, v[2:3]
	s_add_i32 s35, s52, 20
	s_add_i32 s34, s19, 20
	v_or_b32_e32 v54, s35, v0
	v_or_b32_e32 v47, s34, v1
	v_add_u32_e32 v52, v54, v46
	v_add_u32_e32 v50, v47, v3
	v_ashrrev_i32_e32 v53, 31, v52
	v_ashrrev_i32_e32 v51, 31, v50
	v_lshlrev_b64 v[52:53], 12, v[52:53]
	v_lshlrev_b64 v[50:51], 12, v[50:51]
	v_lshl_add_u64 v[52:53], v[48:49], 0, v[52:53]
	v_lshl_add_u64 v[50:51], v[48:49], 0, v[50:51]
	global_load_dword v126, v[52:53], off
	global_load_dword v127, v[50:51], off
	v_mad_u64_u32 v[128:129], s[34:35], v54, s30, v[2:3]
	v_mad_u64_u32 v[130:131], s[34:35], v47, s30, v[2:3]
	s_add_i32 s35, s52, 24
	s_add_i32 s34, s19, 24
	v_or_b32_e32 v54, s35, v0
	v_or_b32_e32 v47, s34, v1
	s_add_i32 s52, s52, 28
	s_add_i32 s19, s19, 28
	s_cmp_lg_u32 s18, 0
	v_add_u32_e32 v52, v54, v46
	v_add_u32_e32 v50, v47, v3
	v_ashrrev_i32_e32 v53, 31, v52
	v_ashrrev_i32_e32 v51, 31, v50
	v_lshlrev_b64 v[52:53], 12, v[52:53]
	v_lshlrev_b64 v[50:51], 12, v[50:51]
	v_lshl_add_u64 v[52:53], v[48:49], 0, v[52:53]
	v_lshl_add_u64 v[50:51], v[48:49], 0, v[50:51]
	global_load_dword v132, v[52:53], off
	global_load_dword v133, v[50:51], off
	v_mad_u64_u32 v[134:135], s[34:35], v54, s30, v[2:3]
	v_mad_u64_u32 v[136:137], s[34:35], v47, s30, v[2:3]
	v_or_b32_e32 v54, s52, v0
	v_or_b32_e32 v47, s19, v1
	v_add_u32_e32 v52, v54, v46
	v_add_u32_e32 v50, v47, v3
	v_ashrrev_i32_e32 v53, 31, v52
	v_ashrrev_i32_e32 v51, 31, v50
	v_lshlrev_b64 v[52:53], 12, v[52:53]
	v_lshlrev_b64 v[50:51], 12, v[50:51]
	v_lshl_add_u64 v[52:53], v[48:49], 0, v[52:53]
	v_lshl_add_u64 v[50:51], v[48:49], 0, v[50:51]
	global_load_dword v138, v[52:53], off
	global_load_dword v139, v[50:51], off
	v_mad_u64_u32 v[140:141], s[34:35], v54, s30, v[2:3]
	v_mad_u64_u32 v[142:143], s[34:35], v47, s30, v[2:3]
	s_waitcnt vmcnt(0)
	ds_write_b32 v98, v96
	ds_write_b32 v100, v97
	ds_write_b32 v104, v102
	ds_write_b32 v106, v103
	ds_write_b32 v110, v108
	ds_write_b32 v112, v109
	ds_write_b32 v116, v114
	ds_write_b32 v118, v115
	ds_write_b32 v122, v120
	ds_write_b32 v124, v121
	ds_write_b32 v128, v126
	ds_write_b32 v130, v127
	ds_write_b32 v134, v132
	ds_write_b32 v136, v133
	ds_write_b32 v140, v138
	ds_write_b32 v142, v139
	s_cbranch_scc1 .LBB0_587
; #define LAS __attribute__((address_space(3)))
; __device__ __forceinline__ unsigned pk2(float lo, float hi) { const f32x2v v = {lo, hi}; return __builtin_bit_cast(unsigned, __builtin_convertvector(v, bf16x2_hw)); }
;     ...
;     for (int j = 0; j < 4; ++j) { const int n = (lane >> 3) + 8 * j; const LAS float* s = scr + (8 * c) * 33 + n;
;         u32x4v o; o.x = pk2(s[0 * 33], s[1 * 33]); o.y = pk2(s[2 * 33], s[3 * 33]); o.z = pk2(s[4 * 33], s[5 * 33]); o.w = pk2(s[6 * 33], s[7 * 33]);
;         *(u32x4v*)(WT + (size_t)(drow0 + n) * ldt + kdst + k0 + 8 * c) = o; }
;     asm volatile("s_waitcnt lgkmcnt(0)" ::: "memory");
	s_waitcnt lgkmcnt(0)
	ds_read2_b32 v[52:53], v68 offset0:33 offset1:41
	ds_read2_b32 v[54:55], v68 offset1:8
	ds_read2_b32 v[56:57], v68 offset0:66 offset1:74
	ds_read2_b32 v[58:59], v68 offset0:99 offset1:107
	ds_read2_b32 v[60:61], v68 offset0:132 offset1:140
	ds_read2_b32 v[62:63], v68 offset0:165 offset1:173
	ds_read2_b32 v[64:65], v68 offset0:198 offset1:206
	ds_read2_b32 v[92:93], v68 offset0:231 offset1:239
	v_mov_b32_e32 v47, v145
	v_or_b32_e32 v3, v90, v67
	v_lshl_add_u64 v[50:51], v[46:47], 1, v[4:5]
	v_lshlrev_b32_e32 v144, 9, v3
	v_or_b32_e32 v3, v90, v69
	s_waitcnt lgkmcnt(6)
	v_cvt_pk_bf16_f32 v46, v54, v52
	s_waitcnt lgkmcnt(4)
	v_cvt_pk_bf16_f32 v47, v56, v58
	s_waitcnt lgkmcnt(2)
	v_cvt_pk_bf16_f32 v48, v60, v62
	s_waitcnt lgkmcnt(0)
	v_cvt_pk_bf16_f32 v49, v64, v92
	v_lshl_add_u64 v[94:95], v[50:51], 0, v[144:145]
	v_lshlrev_b32_e32 v144, 9, v3
	global_store_dwordx4 v[94:95], v[46:49], off
	v_or_b32_e32 v3, v90, v70
	s_nop 0
	v_cvt_pk_bf16_f32 v46, v55, v53
	v_cvt_pk_bf16_f32 v47, v57, v59
	v_cvt_pk_bf16_f32 v48, v61, v63
	v_cvt_pk_bf16_f32 v49, v65, v93
	v_lshl_add_u64 v[52:53], v[50:51], 0, v[144:145]
	global_store_dwordx4 v[52:53], v[46:49], off
	ds_read2_b32 v[52:53], v68 offset0:49 offset1:57
	ds_read2_b32 v[54:55], v68 offset0:16 offset1:24
	ds_read2_b32 v[56:57], v68 offset0:82 offset1:90
	ds_read2_b32 v[58:59], v68 offset0:115 offset1:123
	ds_read2_b32 v[60:61], v68 offset0:148 offset1:156
	ds_read2_b32 v[62:63], v68 offset0:181 offset1:189
	ds_read2_b32 v[64:65], v68 offset0:214 offset1:222
	ds_read2_b32 v[92:93], v68 offset0:247 offset1:255
	v_lshlrev_b32_e32 v144, 9, v3
	v_or_b32_e32 v3, v90, v71
	s_waitcnt lgkmcnt(6)
	v_cvt_pk_bf16_f32 v46, v54, v52
	s_waitcnt lgkmcnt(4)
	v_cvt_pk_bf16_f32 v47, v56, v58
	s_waitcnt lgkmcnt(2)
	v_cvt_pk_bf16_f32 v48, v60, v62
	s_waitcnt lgkmcnt(0)
	v_cvt_pk_bf16_f32 v49, v64, v92
	v_lshl_add_u64 v[94:95], v[50:51], 0, v[144:145]
	v_lshlrev_b32_e32 v144, 9, v3
	global_store_dwordx4 v[94:95], v[46:49], off
	v_lshl_add_u64 v[50:51], v[50:51], 0, v[144:145]
	s_nop 0
	v_cvt_pk_bf16_f32 v46, v55, v53
	v_cvt_pk_bf16_f32 v47, v57, v59
	v_cvt_pk_bf16_f32 v48, v61, v63
	v_cvt_pk_bf16_f32 v49, v65, v93
	global_store_dwordx4 v[50:51], v[46:49], off
	s_waitcnt lgkmcnt(0)

;     ...
;     for (int i = 0; i < 32; ++i) { const int kk = 2 * i + (lane >> 5); float v = W[(size_t)(k0 + kk) * ldw + n0src + (lane & 31)]; if (gain) v *= gain[k0 + kk]; scr[kk * 33 + (lane & 31)] = v; }
; __device__ __forceinline__ void convert_weights(const Params& P, LAS unsigned char* lds, int gw, int NGW, int it0, int it1) {
;     ...
;         if (r < I_PG) { const int kb = r / 32, nb = r % 32; transpose_item(P.in[26], DM, kb * 64, nb * 32, (bf16*)(ws + WS_WPG), DM, nb * 32, P.in[25], scr, lane); continue; } r -= I_PG;
.LBB0_592:
	v_lshl_add_u64 v[140:141], v[48:49], 0, s[18:19]
	global_load_dword v96, v[140:141], off
	v_lshl_add_u64 v[140:141], v[60:61], 0, s[18:19]
	global_load_dword v97, v[140:141], off
	v_lshl_add_u64 v[140:141], v[64:65], 0, s[18:19]
	global_load_dword v98, v[140:141], off
	v_lshl_add_u64 v[140:141], v[62:63], 0, s[18:19]
	global_load_dword v99, v[140:141], off
	v_lshl_add_u64 v[140:141], v[58:59], 0, s[18:19]
	global_load_dword v100, v[140:141], off
	v_lshl_add_u64 v[140:141], v[54:55], 0, s[18:19]
	global_load_dword v101, v[140:141], off
	v_lshl_add_u64 v[140:141], v[50:51], 0, s[18:19]
	global_load_dword v102, v[140:141], off
	v_lshl_add_u64 v[140:141], v[46:47], 0, s[18:19]
	global_load_dword v103, v[140:141], off
	s_add_u32 s18, s18, 0x10000
	s_addc_u32 s19, s19, 0
	v_lshl_add_u64 v[140:141], v[48:49], 0, s[18:19]
	global_load_dword v104, v[140:141], off
	v_lshl_add_u64 v[140:141], v[60:61], 0, s[18:19]
	global_load_dword v105, v[140:141], off
	v_lshl_add_u64 v[140:141], v[64:65], 0, s[18:19]
	global_load_dword v106, v[140:141], off
	v_lshl_add_u64 v[140:141], v[62:63], 0, s[18:19]
	global_load_dword v107, v[140:141], off
	v_lshl_add_u64 v[140:141], v[58:59], 0, s[18:19]
	global_load_dword v108, v[140:141], off
	v_lshl_add_u64 v[140:141], v[54:55], 0, s[18:19]
	global_load_dword v109, v[140:141], off
	v_lshl_add_u64 v[140:141], v[50:51], 0, s[18:19]
	global_load_dword v110, v[140:141], off
	v_lshl_add_u64 v[140:141], v[46:47], 0, s[18:19]
	global_load_dword v111, v[140:141], off
	s_add_u32 s18, s18, 0x10000
	s_addc_u32 s19, s19, 0
	v_lshl_add_u64 v[140:141], v[48:49], 0, s[18:19]
	global_load_dword v112, v[140:141], off
	v_lshl_add_u64 v[140:141], v[60:61], 0, s[18:19]
	global_load_dword v113, v[140:141], off
	v_lshl_add_u64 v[140:141], v[64:65], 0, s[18:19]
	global_load_dword v114, v[140:141], off
	v_lshl_add_u64 v[140:141], v[62:63], 0, s[18:19]
	global_load_dword v115, v[140:141], off
	v_lshl_add_u64 v[140:141], v[58:59], 0, s[18:19]
	global_load_dword v116, v[140:141], off
	v_lshl_add_u64 v[140:141], v[54:55], 0, s[18:19]
	global_load_dword v117, v[140:141], off
	v_lshl_add_u64 v[140:141], v[50:51], 0, s[18:19]
	global_load_dword v118, v[140:141], off
	v_lshl_add_u64 v[140:141], v[46:47], 0, s[18:19]
	global_load_dword v119, v[140:141], off
	s_add_u32 s18, s18, 0x10000
	s_addc_u32 s19, s19, 0
	v_lshl_add_u64 v[140:141], v[48:49], 0, s[18:19]
	global_load_dword v120, v[140:141], off
	v_lshl_add_u64 v[140:141], v[60:61], 0, s[18:19]
	global_load_dword v121, v[140:141], off
	v_lshl_add_u64 v[140:141], v[64:65], 0, s[18:19]
	global_load_dword v122, v[140:141], off
	v_lshl_add_u64 v[140:141], v[62:63], 0, s[18:19]
	global_load_dword v123, v[140:141], off
	v_lshl_add_u64 v[140:141], v[58:59], 0, s[18:19]
	global_load_dword v124, v[140:141], off
	v_lshl_add_u64 v[140:141], v[54:55], 0, s[18:19]
	global_load_dword v125, v[140:141], off
	v_lshl_add_u64 v[140:141], v[50:51], 0, s[18:19]
	global_load_dword v126, v[140:141], off
	v_lshl_add_u64 v[140:141], v[46:47], 0, s[18:19]
	global_load_dword v127, v[140:141], off
	s_andn2_b64 vcc, exec, s[34:35]
	s_cbranch_vccnz .Lcwg0_nogain
	global_load_dword v176, v[52:53], off
	global_load_dword v177, v[56:57], off
	global_load_dword v178, v[56:57], off offset:8
	global_load_dword v179, v[56:57], off offset:16
	global_load_dword v180, v[56:57], off offset:24
	global_load_dword v181, v[56:57], off offset:32
	global_load_dword v182, v[56:57], off offset:40
	global_load_dword v183, v[56:57], off offset:48
	global_load_dword v184, v[52:53], off offset:64
	global_load_dword v185, v[56:57], off offset:64
	global_load_dword v186, v[56:57], off offset:72
	global_load_dword v187, v[56:57], off offset:80
	global_load_dword v188, v[56:57], off offset:88
	global_load_dword v189, v[56:57], off offset:96
	global_load_dword v190, v[56:57], off offset:104
	global_load_dword v191, v[56:57], off offset:112
	global_load_dword v192, v[52:53], off offset:128
	global_load_dword v193, v[56:57], off offset:128
	global_load_dword v194, v[56:57], off offset:136
	global_load_dword v195, v[56:57], off offset:144
	global_load_dword v196, v[56:57], off offset:152
	global_load_dword v197, v[56:57], off offset:160
	global_load_dword v198, v[56:57], off offset:168
	global_load_dword v199, v[56:57], off offset:176
	global_load_dword v200, v[52:53], off offset:192
	global_load_dword v201, v[56:57], off offset:192
	global_load_dword v202, v[56:57], off offset:200
	global_load_dword v203, v[56:57], off offset:208
	global_load_dword v204, v[56:57], off offset:216
	global_load_dword v205, v[56:57], off offset:224
	global_load_dword v206, v[56:57], off offset:232
	global_load_dword v207, v[56:57], off offset:240
	s_waitcnt vmcnt(0)
	v_mul_f32_e32 v96, v96, v176
	v_mul_f32_e32 v97, v97, v177
	v_mul_f32_e32 v98, v98, v178
	v_mul_f32_e32 v99, v99, v179
	v_mul_f32_e32 v100, v100, v180
	v_mul_f32_e32 v101, v101, v181
	v_mul_f32_e32 v102, v102, v182
	v_mul_f32_e32 v103, v103, v183
	v_mul_f32_e32 v104, v104, v184
	v_mul_f32_e32 v105, v105, v185
	v_mul_f32_e32 v106, v106, v186
	v_mul_f32_e32 v107, v107, v187
	v_mul_f32_e32 v108, v108, v188
	v_mul_f32_e32 v109, v109, v189
	v_mul_f32_e32 v110, v110, v190
	v_mul_f32_e32 v111, v111, v191
	v_mul_f32_e32 v112, v112, v192
	v_mul_f32_e32 v113, v113, v193
	v_mul_f32_e32 v114, v114, v194
	v_mul_f32_e32 v115, v115, v195
	v_mul_f32_e32 v116, v116, v196
	v_mul_f32_e32 v117, v117, v197
	v_mul_f32_e32 v118, v118, v198
	v_mul_f32_e32 v119, v119, v199
	v_mul_f32_e32 v120, v120, v200
	v_mul_f32_e32 v121, v121, v201
	v_mul_f32_e32 v122, v122, v202
	v_mul_f32_e32 v123, v123, v203
	v_mul_f32_e32 v124, v124, v204
	v_mul_f32_e32 v125, v125, v205
	v_mul_f32_e32 v126, v126, v206
	v_mul_f32_e32 v127, v127, v207
.Lcwg0_nogain:
	s_waitcnt vmcnt(0)
	ds_write_b32 v91, v96
	ds_write_b32 v91, v97 offset:264
	ds_write_b32 v91, v98 offset:528
	ds_write_b32 v91, v99 offset:792
	ds_write_b32 v91, v100 offset:1056
	ds_write_b32 v91, v101 offset:1320
	ds_write_b32 v91, v102 offset:1584
	ds_write_b32 v91, v103 offset:1848
	ds_write_b32 v91, v104 offset:2112
	ds_write_b32 v91, v105 offset:2376
	ds_write_b32 v91, v106 offset:2640
	ds_write_b32 v91, v107 offset:2904
	ds_write_b32 v91, v108 offset:3168
	ds_write_b32 v91, v109 offset:3432
	ds_write_b32 v91, v110 offset:3696
	ds_write_b32 v91, v111 offset:3960
	ds_write_b32 v91, v112 offset:4224
	ds_write_b32 v91, v113 offset:4488
	ds_write_b32 v91, v114 offset:4752
	ds_write_b32 v91, v115 offset:5016
	ds_write_b32 v91, v116 offset:5280
	ds_write_b32 v91, v117 offset:5544
	ds_write_b32 v91, v118 offset:5808
	ds_write_b32 v91, v119 offset:6072
	ds_write_b32 v91, v120 offset:6336
	ds_write_b32 v91, v121 offset:6600
	ds_write_b32 v91, v122 offset:6864
	ds_write_b32 v91, v123 offset:7128
	ds_write_b32 v91, v124 offset:7392
	ds_write_b32 v91, v125 offset:7656
	ds_write_b32 v91, v126 offset:7920
	ds_write_b32 v91, v127 offset:8184
	s_branch .LBB0_608

;     ...
;     for (int i = 0; i < 32; ++i) { const int kk = 2 * i + (lane >> 5); float v = W[(size_t)(k0 + kk) * ldw + n0src + (lane & 31)]; if (gain) v *= gain[k0 + kk]; scr[kk * 33 + (lane & 31)] = v; }
; __device__ __forceinline__ void convert_weights(const Params& P, LAS unsigned char* lds, int gw, int NGW, int it0, int it1) {
;     ...
;         if (r < I_D) { const int kb = r / 32, nb = r % 32; transpose_item(P.in[24], DM, kb * 64, nb * 32, (bf16*)(ws + WS_WD), DFF, nb * 32, nullptr, scr, lane); continue; } r -= I_D;
.LBB0_612:
	s_lshl_b32 s50, s15, 1
	s_lshl_b32 s19, s14, 1
	v_or_b32_e32 v51, s50, v0
	v_or_b32_e32 v47, s19, v1
	v_add_u32_e32 v54, v51, v46
	v_add_u32_e32 v52, v47, v3
	v_ashrrev_i32_e32 v55, 31, v54
	v_ashrrev_i32_e32 v53, 31, v52
	v_lshlrev_b64 v[54:55], 12, v[54:55]
	v_lshlrev_b64 v[52:53], 12, v[52:53]
	v_lshl_add_u64 v[54:55], v[48:49], 0, v[54:55]
	v_lshl_add_u64 v[52:53], v[48:49], 0, v[52:53]
	global_load_dword v96, v[54:55], off
	global_load_dword v97, v[52:53], off
	v_mad_u64_u32 v[98:99], s[34:35], v51, s30, v[2:3]
	v_mad_u64_u32 v[100:101], s[34:35], v47, s30, v[2:3]
	s_add_i32 s35, s50, 4
	s_add_i32 s34, s19, 4
	v_or_b32_e32 v51, s35, v0
	v_or_b32_e32 v47, s34, v1
	s_add_i32 s15, s15, 16
	s_add_i32 s14, s14, 16
	s_add_i32 s18, s18, -16
	v_add_u32_e32 v54, v51, v46
	v_add_u32_e32 v52, v47, v3
	v_ashrrev_i32_e32 v55, 31, v54
	v_ashrrev_i32_e32 v53, 31, v52
	v_lshlrev_b64 v[54:55], 12, v[54:55]
	v_lshlrev_b64 v[52:53], 12, v[52:53]
	v_lshl_add_u64 v[54:55], v[48:49], 0, v[54:55]
	v_lshl_add_u64 v[52:53], v[48:49], 0, v[52:53]
	global_load_dword v102, v[54:55], off
	global_load_dword v103, v[52:53], off
	v_mad_u64_u32 v[104:105], s[34:35], v51, s30, v[2:3]
	v_mad_u64_u32 v[106:107], s[34:35], v47, s30, v[2:3]
	s_add_i32 s35, s50, 8
	s_add_i32 s34, s19, 8
	v_or_b32_e32 v51, s35, v0
	v_or_b32_e32 v47, s34, v1
	v_add_u32_e32 v54, v51, v46
	v_add_u32_e32 v52, v47, v3
	v_ashrrev_i32_e32 v55, 31, v54
	v_ashrrev_i32_e32 v53, 31, v52
	v_lshlrev_b64 v[54:55], 12, v[54:55]
	v_lshlrev_b64 v[52:53], 12, v[52:53]
	v_lshl_add_u64 v[54:55], v[48:49], 0, v[54:55]
	v_lshl_add_u64 v[52:53], v[48:49], 0, v[52:53]
	global_load_dword v108, v[54:55], off
	global_load_dword v109, v[52:53], off
	v_mad_u64_u32 v[110:111], s[34:35], v51, s30, v[2:3]
	v_mad_u64_u32 v[112:113], s[34:35], v47, s30, v[2:3]
	s_add_i32 s35, s50, 12
	s_add_i32 s34, s19, 12
	v_or_b32_e32 v51, s35, v0
	v_or_b32_e32 v47, s34, v1
	v_add_u32_e32 v54, v51, v46
	v_add_u32_e32 v52, v47, v3
	v_ashrrev_i32_e32 v55, 31, v54
	v_ashrrev_i32_e32 v53, 31, v52
	v_lshlrev_b64 v[54:55], 12, v[54:55]
	v_lshlrev_b64 v[52:53], 12, v[52:53]
	v_lshl_add_u64 v[54:55], v[48:49], 0, v[54:55]
	v_lshl_add_u64 v[52:53], v[48:49], 0, v[52:53]
	global_load_dword v114, v[54:55], off
	global_load_dword v115, v[52:53], off
	v_mad_u64_u32 v[116:117], s[34:35], v51, s30, v[2:3]
	v_mad_u64_u32 v[118:119], s[34:35], v47, s30, v[2:3]
	s_add_i32 s35, s50, 16
	s_add_i32 s34, s19, 16
	v_or_b32_e32 v51, s35, v0
	v_or_b32_e32 v47, s34, v1
	v_add_u32_e32 v54, v51, v46
	v_add_u32_e32 v52, v47, v3
	v_ashrrev_i32_e32 v55, 31, v54
	v_ashrrev_i32_e32 v53, 31, v52
	v_lshlrev_b64 v[54:55], 12, v[54:55]
	v_lshlrev_b64 v[52:53], 12, v[52:53]
	v_lshl_add_u64 v[54:55], v[48:49], 0, v[54:55]
	v_lshl_add_u64 v[52:53], v[48:49], 0, v[52:53]
	global_load_dword v120, v[54:55], off
	global_load_dword v121, v[52:53], off
	v_mad_u64_u32 v[122:123], s[34:35], v51, s30, v[2:3]
	v_mad_u64_u32 v[124:125], s[34:35], v47, s30, v[2:3]
	s_add_i32 s35, s50, 20
	s_add_i32 s34, s19, 20
	v_or_b32_e32 v51, s35, v0
	v_or_b32_e32 v47, s34, v1
	v_add_u32_e32 v54, v51, v46
	v_add_u32_e32 v52, v47, v3
	v_ashrrev_i32_e32 v55, 31, v54
	v_ashrrev_i32_e32 v53, 31, v52
	v_lshlrev_b64 v[54:55], 12, v[54:55]
	v_lshlrev_b64 v[52:53], 12, v[52:53]
	v_lshl_add_u64 v[54:55], v[48:49], 0, v[54:55]
	v_lshl_add_u64 v[52:53], v[48:49], 0, v[52:53]
	global_load_dword v126, v[54:55], off
	global_load_dword v127, v[52:53], off
	v_mad_u64_u32 v[128:129], s[34:35], v51, s30, v[2:3]
	v_mad_u64_u32 v[130:131], s[34:35], v47, s30, v[2:3]
	s_add_i32 s35, s50, 24
	s_add_i32 s34, s19, 24
	v_or_b32_e32 v51, s35, v0
	v_or_b32_e32 v47, s34, v1
	s_add_i32 s50, s50, 28
	s_add_i32 s19, s19, 28
	s_cmp_lg_u32 s18, 0
	v_add_u32_e32 v54, v51, v46
	v_add_u32_e32 v52, v47, v3
	v_ashrrev_i32_e32 v55, 31, v54
	v_ashrrev_i32_e32 v53, 31, v52
	v_lshlrev_b64 v[54:55], 12, v[54:55]
	v_lshlrev_b64 v[52:53], 12, v[52:53]
	v_lshl_add_u64 v[54:55], v[48:49], 0, v[54:55]
	v_lshl_add_u64 v[52:53], v[48:49], 0, v[52:53]
	global_load_dword v132, v[54:55], off
	global_load_dword v133, v[52:53], off
	v_mad_u64_u32 v[134:135], s[34:35], v51, s30, v[2:3]
	v_mad_u64_u32 v[136:137], s[34:35], v47, s30, v[2:3]
	v_or_b32_e32 v51, s50, v0
	v_or_b32_e32 v47, s19, v1
	v_add_u32_e32 v54, v51, v46
	v_add_u32_e32 v52, v47, v3
	v_ashrrev_i32_e32 v55, 31, v54
	v_ashrrev_i32_e32 v53, 31, v52
	v_lshlrev_b64 v[54:55], 12, v[54:55]
	v_lshlrev_b64 v[52:53], 12, v[52:53]
	v_lshl_add_u64 v[54:55], v[48:49], 0, v[54:55]
	v_lshl_add_u64 v[52:53], v[48:49], 0, v[52:53]
	global_load_dword v138, v[54:55], off
	global_load_dword v139, v[52:53], off
	v_mad_u64_u32 v[140:141], s[34:35], v51, s30, v[2:3]
	v_mad_u64_u32 v[142:143], s[34:35], v47, s30, v[2:3]
	s_waitcnt vmcnt(0)
	ds_write_b32 v98, v96
	ds_write_b32 v100, v97
	ds_write_b32 v104, v102
	ds_write_b32 v106, v103
	ds_write_b32 v110, v108
	ds_write_b32 v112, v109
	ds_write_b32 v116, v114
	ds_write_b32 v118, v115
	ds_write_b32 v122, v120
	ds_write_b32 v124, v121
	ds_write_b32 v128, v126
	ds_write_b32 v130, v127
	ds_write_b32 v134, v132
	ds_write_b32 v136, v133
	ds_write_b32 v140, v138
	ds_write_b32 v142, v139
	s_cbranch_scc1 .LBB0_612
; #define LAS __attribute__((address_space(3)))
; __device__ __forceinline__ unsigned pk2(float lo, float hi) { const f32x2v v = {lo, hi}; return __builtin_bit_cast(unsigned, __builtin_convertvector(v, bf16x2_hw)); }
;     ...
;     for (int j = 0; j < 4; ++j) { const int n = (lane >> 3) + 8 * j; const LAS float* s = scr + (8 * c) * 33 + n;
;         u32x4v o; o.x = pk2(s[0 * 33], s[1 * 33]); o.y = pk2(s[2 * 33], s[3 * 33]); o.z = pk2(s[4 * 33], s[5 * 33]); o.w = pk2(s[6 * 33], s[7 * 33]);
;         *(u32x4v*)(WT + (size_t)(drow0 + n) * ldt + kdst + k0 + 8 * c) = o; }
;     asm volatile("s_waitcnt lgkmcnt(0)" ::: "memory");
	s_waitcnt lgkmcnt(0)
	ds_read2_b32 v[54:55], v68 offset0:33 offset1:41
	ds_read2_b32 v[56:57], v68 offset1:8
	ds_read2_b32 v[58:59], v68 offset0:66 offset1:74
	ds_read2_b32 v[60:61], v68 offset0:99 offset1:107
	ds_read2_b32 v[62:63], v68 offset0:132 offset1:140
	ds_read2_b32 v[64:65], v68 offset0:165 offset1:173
	ds_read2_b32 v[90:91], v68 offset0:198 offset1:206
	ds_read2_b32 v[92:93], v68 offset0:231 offset1:239
	v_or_b32_e32 v3, v50, v67
	v_mul_u32_u24_e32 v3, 0xb00, v3
	v_mov_b32_e32 v47, v145
	v_lshlrev_b32_e32 v144, 1, v3
	v_or_b32_e32 v3, v50, v69
	v_lshl_add_u64 v[52:53], v[46:47], 1, v[8:9]
	v_mul_u32_u24_e32 v3, 0xb00, v3
	s_waitcnt lgkmcnt(6)
	v_cvt_pk_bf16_f32 v46, v56, v54
	s_waitcnt lgkmcnt(4)
	v_cvt_pk_bf16_f32 v47, v58, v60
	s_waitcnt lgkmcnt(2)
	v_cvt_pk_bf16_f32 v48, v62, v64
	s_waitcnt lgkmcnt(0)
	v_cvt_pk_bf16_f32 v49, v90, v92
	v_lshl_add_u64 v[94:95], v[52:53], 0, v[144:145]
	v_lshlrev_b32_e32 v144, 1, v3
	global_store_dwordx4 v[94:95], v[46:49], off
	v_or_b32_e32 v3, v50, v70
	v_mul_u32_u24_e32 v3, 0xb00, v3
	v_cvt_pk_bf16_f32 v46, v57, v55
	v_cvt_pk_bf16_f32 v47, v59, v61
	v_cvt_pk_bf16_f32 v48, v63, v65
	v_cvt_pk_bf16_f32 v49, v91, v93
	v_lshl_add_u64 v[54:55], v[52:53], 0, v[144:145]
	global_store_dwordx4 v[54:55], v[46:49], off
	ds_read2_b32 v[54:55], v68 offset0:16 offset1:24
	ds_read2_b32 v[56:57], v68 offset0:49 offset1:57
	ds_read2_b32 v[58:59], v68 offset0:82 offset1:90
	ds_read2_b32 v[60:61], v68 offset0:115 offset1:123
	ds_read2_b32 v[62:63], v68 offset0:148 offset1:156
	ds_read2_b32 v[64:65], v68 offset0:181 offset1:189
	ds_read2_b32 v[90:91], v68 offset0:214 offset1:222
	ds_read2_b32 v[92:93], v68 offset0:247 offset1:255
	v_lshlrev_b32_e32 v144, 1, v3
	v_or_b32_e32 v3, v50, v71
	v_mul_u32_u24_e32 v3, 0xb00, v3
	s_waitcnt lgkmcnt(6)
	v_cvt_pk_bf16_f32 v46, v54, v56
	s_waitcnt lgkmcnt(4)
	v_cvt_pk_bf16_f32 v47, v58, v60
	s_waitcnt lgkmcnt(2)
	v_cvt_pk_bf16_f32 v48, v62, v64
	s_waitcnt lgkmcnt(0)
	v_cvt_pk_bf16_f32 v49, v90, v92
	v_lshl_add_u64 v[94:95], v[52:53], 0, v[144:145]
	v_lshlrev_b32_e32 v144, 1, v3
	global_store_dwordx4 v[94:95], v[46:49], off
	v_lshl_add_u64 v[50:51], v[52:53], 0, v[144:145]
	s_nop 0
	v_cvt_pk_bf16_f32 v46, v55, v57
	v_cvt_pk_bf16_f32 v47, v59, v61
	v_cvt_pk_bf16_f32 v48, v63, v65
	v_cvt_pk_bf16_f32 v49, v91, v93
	global_store_dwordx4 v[50:51], v[46:49], off
	s_waitcnt lgkmcnt(0)

;     ...
;     for (int i = 0; i < 32; ++i) { const int kk = 2 * i + (lane >> 5); float v = W[(size_t)(k0 + kk) * ldw + n0src + (lane & 31)]; if (gain) v *= gain[k0 + kk]; scr[kk * 33 + (lane & 31)] = v; }
; __device__ __forceinline__ void convert_weights(const Params& P, LAS unsigned char* lds, int gw, int NGW, int it0, int it1) {
;     ...
;         if (r < I_G) { const int kb = r / 88, nb = r % 88, n0 = nb * 32; transpose_item(P.in[22], DFF, kb * 64, n0, (bf16*)(ws + WS_WGU), DM, 256 * (n0 >> 7) + (n0 & 127), P.in[21], scr, lane); continue; } r -= I_G;
;         if (r < I_U) { const int kb = r / 88, nb = r % 88, n0 = nb * 32; transpose_item(P.in[23], DFF, kb * 64, n0, (bf16*)(ws + WS_WGU), DM, 256 * (n0 >> 7) + 128 + (n0 & 127), P.in[21], scr, lane); continue; } r -= I_U;
.LBB0_618:
	v_lshl_add_u64 v[140:141], v[48:49], 0, s[18:19]
	global_load_dword v96, v[140:141], off
	v_lshl_add_u64 v[140:141], v[62:63], 0, s[18:19]
	global_load_dword v97, v[140:141], off
	v_lshl_add_u64 v[140:141], v[60:61], 0, s[18:19]
	global_load_dword v98, v[140:141], off
	v_lshl_add_u64 v[140:141], v[58:59], 0, s[18:19]
	global_load_dword v99, v[140:141], off
	v_lshl_add_u64 v[140:141], v[56:57], 0, s[18:19]
	global_load_dword v100, v[140:141], off
	v_lshl_add_u64 v[140:141], v[54:55], 0, s[18:19]
	global_load_dword v101, v[140:141], off
	v_lshl_add_u64 v[140:141], v[50:51], 0, s[18:19]
	global_load_dword v102, v[140:141], off
	v_lshl_add_u64 v[140:141], v[46:47], 0, s[18:19]
	global_load_dword v103, v[140:141], off
	s_add_u32 s18, s18, 0x2c000
	s_addc_u32 s19, s19, 0
	v_lshl_add_u64 v[140:141], v[48:49], 0, s[18:19]
	global_load_dword v104, v[140:141], off
	v_lshl_add_u64 v[140:141], v[62:63], 0, s[18:19]
	global_load_dword v105, v[140:141], off
	v_lshl_add_u64 v[140:141], v[60:61], 0, s[18:19]
	global_load_dword v106, v[140:141], off
	v_lshl_add_u64 v[140:141], v[58:59], 0, s[18:19]
	global_load_dword v107, v[140:141], off
	v_lshl_add_u64 v[140:141], v[56:57], 0, s[18:19]
	global_load_dword v108, v[140:141], off
	v_lshl_add_u64 v[140:141], v[54:55], 0, s[18:19]
	global_load_dword v109, v[140:141], off
	v_lshl_add_u64 v[140:141], v[50:51], 0, s[18:19]
	global_load_dword v110, v[140:141], off
	v_lshl_add_u64 v[140:141], v[46:47], 0, s[18:19]
	global_load_dword v111, v[140:141], off
	s_add_u32 s18, s18, 0x2c000
	s_addc_u32 s19, s19, 0
	v_lshl_add_u64 v[140:141], v[48:49], 0, s[18:19]
	global_load_dword v112, v[140:141], off
	v_lshl_add_u64 v[140:141], v[62:63], 0, s[18:19]
	global_load_dword v113, v[140:141], off
	v_lshl_add_u64 v[140:141], v[60:61], 0, s[18:19]
	global_load_dword v114, v[140:141], off
	v_lshl_add_u64 v[140:141], v[58:59], 0, s[18:19]
	global_load_dword v115, v[140:141], off
	v_lshl_add_u64 v[140:141], v[56:57], 0, s[18:19]
	global_load_dword v116, v[140:141], off
	v_lshl_add_u64 v[140:141], v[54:55], 0, s[18:19]
	global_load_dword v117, v[140:141], off
	v_lshl_add_u64 v[140:141], v[50:51], 0, s[18:19]
	global_load_dword v118, v[140:141], off
	v_lshl_add_u64 v[140:141], v[46:47], 0, s[18:19]
	global_load_dword v119, v[140:141], off
	s_add_u32 s18, s18, 0x2c000
	s_addc_u32 s19, s19, 0
	v_lshl_add_u64 v[140:141], v[48:49], 0, s[18:19]
	global_load_dword v120, v[140:141], off
	v_lshl_add_u64 v[140:141], v[62:63], 0, s[18:19]
	global_load_dword v121, v[140:141], off
	v_lshl_add_u64 v[140:141], v[60:61], 0, s[18:19]
	global_load_dword v122, v[140:141], off
	v_lshl_add_u64 v[140:141], v[58:59], 0, s[18:19]
	global_load_dword v123, v[140:141], off
	v_lshl_add_u64 v[140:141], v[56:57], 0, s[18:19]
	global_load_dword v124, v[140:141], off
	v_lshl_add_u64 v[140:141], v[54:55], 0, s[18:19]
	global_load_dword v125, v[140:141], off
	v_lshl_add_u64 v[140:141], v[50:51], 0, s[18:19]
	global_load_dword v126, v[140:141], off
	v_lshl_add_u64 v[140:141], v[46:47], 0, s[18:19]
	global_load_dword v127, v[140:141], off
	v_readlane_b32 s34, v252, 54
	v_readlane_b32 s35, v252, 55
	s_nop 3
	s_andn2_b64 vcc, exec, s[34:35]
	s_cbranch_vccnz .Lcwg1_nogain
	global_load_dword v176, v[52:53], off offset:-56
	global_load_dword v177, v[52:53], off offset:-48
	global_load_dword v178, v[52:53], off offset:-40
	global_load_dword v179, v[52:53], off offset:-32
	global_load_dword v180, v[52:53], off offset:-24
	global_load_dword v181, v[52:53], off offset:-16
	global_load_dword v182, v[52:53], off offset:-8
	global_load_dword v183, v[52:53], off
	global_load_dword v184, v[52:53], off offset:8
	global_load_dword v185, v[52:53], off offset:16
	global_load_dword v186, v[52:53], off offset:24
	global_load_dword v187, v[52:53], off offset:32
	global_load_dword v188, v[52:53], off offset:40
	global_load_dword v189, v[52:53], off offset:48
	global_load_dword v190, v[52:53], off offset:56
	global_load_dword v191, v[52:53], off offset:64
	global_load_dword v192, v[52:53], off offset:72
	global_load_dword v193, v[52:53], off offset:80
	global_load_dword v194, v[52:53], off offset:88
	global_load_dword v195, v[52:53], off offset:96
	global_load_dword v196, v[52:53], off offset:104
	global_load_dword v197, v[52:53], off offset:112
	global_load_dword v198, v[52:53], off offset:120
	global_load_dword v199, v[52:53], off offset:128
	global_load_dword v200, v[52:53], off offset:136
	global_load_dword v201, v[52:53], off offset:144
	global_load_dword v202, v[52:53], off offset:152
	global_load_dword v203, v[52:53], off offset:160
	global_load_dword v204, v[52:53], off offset:168
	global_load_dword v205, v[52:53], off offset:176
	global_load_dword v206, v[52:53], off offset:184
	global_load_dword v207, v[52:53], off offset:192
	s_waitcnt vmcnt(0)
	v_mul_f32_e32 v96, v96, v176
	v_mul_f32_e32 v97, v97, v177
	v_mul_f32_e32 v98, v98, v178
	v_mul_f32_e32 v99, v99, v179
	v_mul_f32_e32 v100, v100, v180
	v_mul_f32_e32 v101, v101, v181
	v_mul_f32_e32 v102, v102, v182
	v_mul_f32_e32 v103, v103, v183
	v_mul_f32_e32 v104, v104, v184
	v_mul_f32_e32 v105, v105, v185
	v_mul_f32_e32 v106, v106, v186
	v_mul_f32_e32 v107, v107, v187
	v_mul_f32_e32 v108, v108, v188
	v_mul_f32_e32 v109, v109, v189
	v_mul_f32_e32 v110, v110, v190
	v_mul_f32_e32 v111, v111, v191
	v_mul_f32_e32 v112, v112, v192
	v_mul_f32_e32 v113, v113, v193
	v_mul_f32_e32 v114, v114, v194
	v_mul_f32_e32 v115, v115, v195
	v_mul_f32_e32 v116, v116, v196
	v_mul_f32_e32 v117, v117, v197
	v_mul_f32_e32 v118, v118, v198
	v_mul_f32_e32 v119, v119, v199
	v_mul_f32_e32 v120, v120, v200
	v_mul_f32_e32 v121, v121, v201
	v_mul_f32_e32 v122, v122, v202
	v_mul_f32_e32 v123, v123, v203
	v_mul_f32_e32 v124, v124, v204
	v_mul_f32_e32 v125, v125, v205
	v_mul_f32_e32 v126, v126, v206
	v_mul_f32_e32 v127, v127, v207
.Lcwg1_nogain:
	s_waitcnt vmcnt(0)
	ds_write_b32 v90, v96
	ds_write_b32 v90, v97 offset:264
	ds_write_b32 v90, v98 offset:528
	ds_write_b32 v90, v99 offset:792
	ds_write_b32 v90, v100 offset:1056
	ds_write_b32 v90, v101 offset:1320
	ds_write_b32 v90, v102 offset:1584
	ds_write_b32 v90, v103 offset:1848
	ds_write_b32 v90, v104 offset:2112
	ds_write_b32 v90, v105 offset:2376
	ds_write_b32 v90, v106 offset:2640
	ds_write_b32 v90, v107 offset:2904
	ds_write_b32 v90, v108 offset:3168
	ds_write_b32 v90, v109 offset:3432
	ds_write_b32 v90, v110 offset:3696
	ds_write_b32 v90, v111 offset:3960
	ds_write_b32 v90, v112 offset:4224
	ds_write_b32 v90, v113 offset:4488
	ds_write_b32 v90, v114 offset:4752
	ds_write_b32 v90, v115 offset:5016
	ds_write_b32 v90, v116 offset:5280
	ds_write_b32 v90, v117 offset:5544
	ds_write_b32 v90, v118 offset:5808
	ds_write_b32 v90, v119 offset:6072
	ds_write_b32 v90, v120 offset:6336
	ds_write_b32 v90, v121 offset:6600
	ds_write_b32 v90, v122 offset:6864
	ds_write_b32 v90, v123 offset:7128
	ds_write_b32 v90, v124 offset:7392
	ds_write_b32 v90, v125 offset:7656
	ds_write_b32 v90, v126 offset:7920
	ds_write_b32 v90, v127 offset:8184
	s_branch .LBB0_634

;     ...
;     for (int i = 0; i < 32; ++i) { const int kk = 2 * i + (lane >> 5); float v = W[(size_t)(k0 + kk) * ldw + n0src + (lane & 31)]; if (gain) v *= gain[k0 + kk]; scr[kk * 33 + (lane & 31)] = v; }
; __device__ __forceinline__ void convert_weights(const Params& P, LAS unsigned char* lds, int gw, int NGW, int it0, int it1) {
;     ...
;         if (r < I_O) { const int kb = r / 32, nb = r % 32; transpose_item(P.in[20], DM, kb * 64, nb * 32, (bf16*)(ws + WS_WO), DM, nb * 32, nullptr, scr, lane); continue; } r -= I_O;
.LBB0_659:
	s_lshl_b32 s44, s15, 1
	s_lshl_b32 s19, s14, 1
	v_or_b32_e32 v51, s44, v0
	v_or_b32_e32 v47, s19, v1
	v_add_u32_e32 v54, v51, v46
	v_add_u32_e32 v52, v47, v3
	v_ashrrev_i32_e32 v55, 31, v54
	v_ashrrev_i32_e32 v53, 31, v52
	v_lshlrev_b64 v[54:55], 12, v[54:55]
	v_lshlrev_b64 v[52:53], 12, v[52:53]
	v_lshl_add_u64 v[54:55], v[48:49], 0, v[54:55]
	v_lshl_add_u64 v[52:53], v[48:49], 0, v[52:53]
	global_load_dword v96, v[54:55], off
	global_load_dword v97, v[52:53], off
	v_mad_u64_u32 v[98:99], s[34:35], v51, s30, v[2:3]
	v_mad_u64_u32 v[100:101], s[34:35], v47, s30, v[2:3]
	s_add_i32 s35, s44, 4
	s_add_i32 s34, s19, 4
	v_or_b32_e32 v51, s35, v0
	v_or_b32_e32 v47, s34, v1
	s_add_i32 s15, s15, 16
	s_add_i32 s14, s14, 16
	s_add_i32 s18, s18, -16
	v_add_u32_e32 v54, v51, v46
	v_add_u32_e32 v52, v47, v3
	v_ashrrev_i32_e32 v55, 31, v54
	v_ashrrev_i32_e32 v53, 31, v52
	v_lshlrev_b64 v[54:55], 12, v[54:55]
	v_lshlrev_b64 v[52:53], 12, v[52:53]
	v_lshl_add_u64 v[54:55], v[48:49], 0, v[54:55]
	v_lshl_add_u64 v[52:53], v[48:49], 0, v[52:53]
	global_load_dword v102, v[54:55], off
	global_load_dword v103, v[52:53], off
	v_mad_u64_u32 v[104:105], s[34:35], v51, s30, v[2:3]
	v_mad_u64_u32 v[106:107], s[34:35], v47, s30, v[2:3]
	s_add_i32 s35, s44, 8
	s_add_i32 s34, s19, 8
	v_or_b32_e32 v51, s35, v0
	v_or_b32_e32 v47, s34, v1
	v_add_u32_e32 v54, v51, v46
	v_add_u32_e32 v52, v47, v3
	v_ashrrev_i32_e32 v55, 31, v54
	v_ashrrev_i32_e32 v53, 31, v52
	v_lshlrev_b64 v[54:55], 12, v[54:55]
	v_lshlrev_b64 v[52:53], 12, v[52:53]
	v_lshl_add_u64 v[54:55], v[48:49], 0, v[54:55]
	v_lshl_add_u64 v[52:53], v[48:49], 0, v[52:53]
	global_load_dword v108, v[54:55], off
	global_load_dword v109, v[52:53], off
	v_mad_u64_u32 v[110:111], s[34:35], v51, s30, v[2:3]
	v_mad_u64_u32 v[112:113], s[34:35], v47, s30, v[2:3]
	s_add_i32 s35, s44, 12
	s_add_i32 s34, s19, 12
	v_or_b32_e32 v51, s35, v0
	v_or_b32_e32 v47, s34, v1
	v_add_u32_e32 v54, v51, v46
	v_add_u32_e32 v52, v47, v3
	v_ashrrev_i32_e32 v55, 31, v54
	v_ashrrev_i32_e32 v53, 31, v52
	v_lshlrev_b64 v[54:55], 12, v[54:55]
	v_lshlrev_b64 v[52:53], 12, v[52:53]
	v_lshl_add_u64 v[54:55], v[48:49], 0, v[54:55]
	v_lshl_add_u64 v[52:53], v[48:49], 0, v[52:53]
	global_load_dword v114, v[54:55], off
	global_load_dword v115, v[52:53], off
	v_mad_u64_u32 v[116:117], s[34:35], v51, s30, v[2:3]
	v_mad_u64_u32 v[118:119], s[34:35], v47, s30, v[2:3]
	s_add_i32 s35, s44, 16
	s_add_i32 s34, s19, 16
	v_or_b32_e32 v51, s35, v0
	v_or_b32_e32 v47, s34, v1
	v_add_u32_e32 v54, v51, v46
	v_add_u32_e32 v52, v47, v3
	v_ashrrev_i32_e32 v55, 31, v54
	v_ashrrev_i32_e32 v53, 31, v52
	v_lshlrev_b64 v[54:55], 12, v[54:55]
	v_lshlrev_b64 v[52:53], 12, v[52:53]
	v_lshl_add_u64 v[54:55], v[48:49], 0, v[54:55]
	v_lshl_add_u64 v[52:53], v[48:49], 0, v[52:53]
	global_load_dword v120, v[54:55], off
	global_load_dword v121, v[52:53], off
	v_mad_u64_u32 v[122:123], s[34:35], v51, s30, v[2:3]
	v_mad_u64_u32 v[124:125], s[34:35], v47, s30, v[2:3]
	s_add_i32 s35, s44, 20
	s_add_i32 s34, s19, 20
	v_or_b32_e32 v51, s35, v0
	v_or_b32_e32 v47, s34, v1
	v_add_u32_e32 v54, v51, v46
	v_add_u32_e32 v52, v47, v3
	v_ashrrev_i32_e32 v55, 31, v54
	v_ashrrev_i32_e32 v53, 31, v52
	v_lshlrev_b64 v[54:55], 12, v[54:55]
	v_lshlrev_b64 v[52:53], 12, v[52:53]
	v_lshl_add_u64 v[54:55], v[48:49], 0, v[54:55]
	v_lshl_add_u64 v[52:53], v[48:49], 0, v[52:53]
	global_load_dword v126, v[54:55], off
	global_load_dword v127, v[52:53], off
	v_mad_u64_u32 v[128:129], s[34:35], v51, s30, v[2:3]
	v_mad_u64_u32 v[130:131], s[34:35], v47, s30, v[2:3]
	s_add_i32 s35, s44, 24
	s_add_i32 s34, s19, 24
	v_or_b32_e32 v51, s35, v0
	v_or_b32_e32 v47, s34, v1
	s_add_i32 s44, s44, 28
	s_add_i32 s19, s19, 28
	s_cmp_lg_u32 s18, 0
	v_add_u32_e32 v54, v51, v46
	v_add_u32_e32 v52, v47, v3
	v_ashrrev_i32_e32 v55, 31, v54
	v_ashrrev_i32_e32 v53, 31, v52
	v_lshlrev_b64 v[54:55], 12, v[54:55]
	v_lshlrev_b64 v[52:53], 12, v[52:53]
	v_lshl_add_u64 v[54:55], v[48:49], 0, v[54:55]
	v_lshl_add_u64 v[52:53], v[48:49], 0, v[52:53]
	global_load_dword v132, v[54:55], off
	global_load_dword v133, v[52:53], off
	v_mad_u64_u32 v[134:135], s[34:35], v51, s30, v[2:3]
	v_mad_u64_u32 v[136:137], s[34:35], v47, s30, v[2:3]
	v_or_b32_e32 v51, s44, v0
	v_or_b32_e32 v47, s19, v1
	v_add_u32_e32 v54, v51, v46
	v_add_u32_e32 v52, v47, v3
	v_ashrrev_i32_e32 v55, 31, v54
	v_ashrrev_i32_e32 v53, 31, v52
	v_lshlrev_b64 v[54:55], 12, v[54:55]
	v_lshlrev_b64 v[52:53], 12, v[52:53]
	v_lshl_add_u64 v[54:55], v[48:49], 0, v[54:55]
	v_lshl_add_u64 v[52:53], v[48:49], 0, v[52:53]
	global_load_dword v138, v[54:55], off
	global_load_dword v139, v[52:53], off
	v_mad_u64_u32 v[140:141], s[34:35], v51, s30, v[2:3]
	v_mad_u64_u32 v[142:143], s[34:35], v47, s30, v[2:3]
	s_waitcnt vmcnt(0)
	ds_write_b32 v98, v96
	ds_write_b32 v100, v97
	ds_write_b32 v104, v102
	ds_write_b32 v106, v103
	ds_write_b32 v110, v108
	ds_write_b32 v112, v109
	ds_write_b32 v116, v114
	ds_write_b32 v118, v115
	ds_write_b32 v122, v120
	ds_write_b32 v124, v121
	ds_write_b32 v128, v126
	ds_write_b32 v130, v127
	ds_write_b32 v134, v132
	ds_write_b32 v136, v133
	ds_write_b32 v140, v138
	ds_write_b32 v142, v139
	s_cbranch_scc1 .LBB0_659
; #define LAS __attribute__((address_space(3)))
; __device__ __forceinline__ unsigned pk2(float lo, float hi) { const f32x2v v = {lo, hi}; return __builtin_bit_cast(unsigned, __builtin_convertvector(v, bf16x2_hw)); }
;     ...
;     for (int j = 0; j < 4; ++j) { const int n = (lane >> 3) + 8 * j; const LAS float* s = scr + (8 * c) * 33 + n;
;         u32x4v o; o.x = pk2(s[0 * 33], s[1 * 33]); o.y = pk2(s[2 * 33], s[3 * 33]); o.z = pk2(s[4 * 33], s[5 * 33]); o.w = pk2(s[6 * 33], s[7 * 33]);
;         *(u32x4v*)(WT + (size_t)(drow0 + n) * ldt + kdst + k0 + 8 * c) = o; }
;     asm volatile("s_waitcnt lgkmcnt(0)" ::: "memory");
	s_waitcnt lgkmcnt(0)
	ds_read2_b32 v[54:55], v68 offset0:33 offset1:41
	ds_read2_b32 v[56:57], v68 offset1:8
	ds_read2_b32 v[58:59], v68 offset0:66 offset1:74
	ds_read2_b32 v[60:61], v68 offset0:99 offset1:107
	ds_read2_b32 v[62:63], v68 offset0:132 offset1:140
	ds_read2_b32 v[64:65], v68 offset0:165 offset1:173
	ds_read2_b32 v[90:91], v68 offset0:198 offset1:206
	ds_read2_b32 v[92:93], v68 offset0:231 offset1:239
	v_mov_b32_e32 v47, v145
	v_or_b32_e32 v3, v50, v67
	v_lshl_add_u64 v[52:53], v[46:47], 1, v[12:13]
	v_lshlrev_b32_e32 v144, 11, v3
	v_or_b32_e32 v3, v50, v69
	s_waitcnt lgkmcnt(6)
	v_cvt_pk_bf16_f32 v46, v56, v54
	s_waitcnt lgkmcnt(4)
	v_cvt_pk_bf16_f32 v47, v58, v60
	s_waitcnt lgkmcnt(2)
	v_cvt_pk_bf16_f32 v48, v62, v64
	s_waitcnt lgkmcnt(0)
	v_cvt_pk_bf16_f32 v49, v90, v92
	v_lshl_add_u64 v[94:95], v[52:53], 0, v[144:145]
	v_lshlrev_b32_e32 v144, 11, v3
	global_store_dwordx4 v[94:95], v[46:49], off
	v_or_b32_e32 v3, v50, v70
	s_nop 0
	v_cvt_pk_bf16_f32 v46, v57, v55
	v_cvt_pk_bf16_f32 v47, v59, v61
	v_cvt_pk_bf16_f32 v48, v63, v65
	v_cvt_pk_bf16_f32 v49, v91, v93
	v_lshl_add_u64 v[54:55], v[52:53], 0, v[144:145]
	global_store_dwordx4 v[54:55], v[46:49], off
	ds_read2_b32 v[54:55], v68 offset0:49 offset1:57
	ds_read2_b32 v[56:57], v68 offset0:16 offset1:24
	ds_read2_b32 v[58:59], v68 offset0:82 offset1:90
	ds_read2_b32 v[60:61], v68 offset0:115 offset1:123
	ds_read2_b32 v[62:63], v68 offset0:148 offset1:156
	ds_read2_b32 v[64:65], v68 offset0:181 offset1:189
	ds_read2_b32 v[90:91], v68 offset0:214 offset1:222
	ds_read2_b32 v[92:93], v68 offset0:247 offset1:255
	v_lshlrev_b32_e32 v144, 11, v3
	v_or_b32_e32 v3, v50, v71
	s_waitcnt lgkmcnt(6)
	v_cvt_pk_bf16_f32 v46, v56, v54
	s_waitcnt lgkmcnt(4)
	v_cvt_pk_bf16_f32 v47, v58, v60
	s_waitcnt lgkmcnt(2)
	v_cvt_pk_bf16_f32 v48, v62, v64
	s_waitcnt lgkmcnt(0)
	v_cvt_pk_bf16_f32 v49, v90, v92
	v_lshl_add_u64 v[94:95], v[52:53], 0, v[144:145]
	v_lshlrev_b32_e32 v144, 11, v3
	global_store_dwordx4 v[94:95], v[46:49], off
	v_lshl_add_u64 v[50:51], v[52:53], 0, v[144:145]
	s_nop 0
	v_cvt_pk_bf16_f32 v46, v57, v55
	v_cvt_pk_bf16_f32 v47, v59, v61
	v_cvt_pk_bf16_f32 v48, v63, v65
	v_cvt_pk_bf16_f32 v49, v91, v93
	global_store_dwordx4 v[50:51], v[46:49], off
	s_waitcnt lgkmcnt(0)

;     ...
;     for (int i = 0; i < 32; ++i) { const int kk = 2 * i + (lane >> 5); float v = W[(size_t)(k0 + kk) * ldw + n0src + (lane & 31)]; if (gain) v *= gain[k0 + kk]; scr[kk * 33 + (lane & 31)] = v; }
; __device__ __forceinline__ void convert_weights(const Params& P, LAS unsigned char* lds, int gw, int NGW, int it0, int it1) {
;     ...
;         if (r < I_A) { const int kb = r / 32, nb = r % 32; transpose_item(P.in[18], DM, kb * 64, nb * 32, (bf16*)(ws + WS_WA), KMIX, nb * 32, nullptr, scr, lane, 0); continue; } r -= I_A;
;         if (r < I_B) { const int kb = r / 32, nb = r % 32; transpose_item(P.in[19], DM, kb * 64, nb * 32, (bf16*)(ws + WS_WA), KMIX, nb * 32, nullptr, scr, lane, 256); continue; } r -= I_B;
.LBB0_664:
	s_lshl_b32 s42, s15, 1
	s_lshl_b32 s19, s14, 1
	v_or_b32_e32 v51, s42, v0
	v_or_b32_e32 v47, s19, v1
	v_add_u32_e32 v54, v51, v46
	v_add_u32_e32 v52, v47, v3
	v_ashrrev_i32_e32 v55, 31, v54
	v_ashrrev_i32_e32 v53, 31, v52
	v_lshlrev_b64 v[54:55], 12, v[54:55]
	v_lshlrev_b64 v[52:53], 12, v[52:53]
	v_lshl_add_u64 v[54:55], v[48:49], 0, v[54:55]
	v_lshl_add_u64 v[52:53], v[48:49], 0, v[52:53]
	global_load_dword v96, v[54:55], off
	global_load_dword v97, v[52:53], off
	v_mad_u64_u32 v[98:99], s[34:35], v51, s30, v[2:3]
	v_mad_u64_u32 v[100:101], s[34:35], v47, s30, v[2:3]
	s_add_i32 s35, s42, 4
	s_add_i32 s34, s19, 4
	v_or_b32_e32 v51, s35, v0
	v_or_b32_e32 v47, s34, v1
	s_add_i32 s15, s15, 16
	s_add_i32 s14, s14, 16
	s_add_i32 s18, s18, -16
	v_add_u32_e32 v54, v51, v46
	v_add_u32_e32 v52, v47, v3
	v_ashrrev_i32_e32 v55, 31, v54
	v_ashrrev_i32_e32 v53, 31, v52
	v_lshlrev_b64 v[54:55], 12, v[54:55]
	v_lshlrev_b64 v[52:53], 12, v[52:53]
	v_lshl_add_u64 v[54:55], v[48:49], 0, v[54:55]
	v_lshl_add_u64 v[52:53], v[48:49], 0, v[52:53]
	global_load_dword v102, v[54:55], off
	global_load_dword v103, v[52:53], off
	v_mad_u64_u32 v[104:105], s[34:35], v51, s30, v[2:3]
	v_mad_u64_u32 v[106:107], s[34:35], v47, s30, v[2:3]
	s_add_i32 s35, s42, 8
	s_add_i32 s34, s19, 8
	v_or_b32_e32 v51, s35, v0
	v_or_b32_e32 v47, s34, v1
	v_add_u32_e32 v54, v51, v46
	v_add_u32_e32 v52, v47, v3
	v_ashrrev_i32_e32 v55, 31, v54
	v_ashrrev_i32_e32 v53, 31, v52
	v_lshlrev_b64 v[54:55], 12, v[54:55]
	v_lshlrev_b64 v[52:53], 12, v[52:53]
	v_lshl_add_u64 v[54:55], v[48:49], 0, v[54:55]
	v_lshl_add_u64 v[52:53], v[48:49], 0, v[52:53]
	global_load_dword v108, v[54:55], off
	global_load_dword v109, v[52:53], off
	v_mad_u64_u32 v[110:111], s[34:35], v51, s30, v[2:3]
	v_mad_u64_u32 v[112:113], s[34:35], v47, s30, v[2:3]
	s_add_i32 s35, s42, 12
	s_add_i32 s34, s19, 12
	v_or_b32_e32 v51, s35, v0
	v_or_b32_e32 v47, s34, v1
	v_add_u32_e32 v54, v51, v46
	v_add_u32_e32 v52, v47, v3
	v_ashrrev_i32_e32 v55, 31, v54
	v_ashrrev_i32_e32 v53, 31, v52
	v_lshlrev_b64 v[54:55], 12, v[54:55]
	v_lshlrev_b64 v[52:53], 12, v[52:53]
	v_lshl_add_u64 v[54:55], v[48:49], 0, v[54:55]
	v_lshl_add_u64 v[52:53], v[48:49], 0, v[52:53]
	global_load_dword v114, v[54:55], off
	global_load_dword v115, v[52:53], off
	v_mad_u64_u32 v[116:117], s[34:35], v51, s30, v[2:3]
	v_mad_u64_u32 v[118:119], s[34:35], v47, s30, v[2:3]
	s_add_i32 s35, s42, 16
	s_add_i32 s34, s19, 16
	v_or_b32_e32 v51, s35, v0
	v_or_b32_e32 v47, s34, v1
	v_add_u32_e32 v54, v51, v46
	v_add_u32_e32 v52, v47, v3
	v_ashrrev_i32_e32 v55, 31, v54
	v_ashrrev_i32_e32 v53, 31, v52
	v_lshlrev_b64 v[54:55], 12, v[54:55]
	v_lshlrev_b64 v[52:53], 12, v[52:53]
	v_lshl_add_u64 v[54:55], v[48:49], 0, v[54:55]
	v_lshl_add_u64 v[52:53], v[48:49], 0, v[52:53]
	global_load_dword v120, v[54:55], off
	global_load_dword v121, v[52:53], off
	v_mad_u64_u32 v[122:123], s[34:35], v51, s30, v[2:3]
	v_mad_u64_u32 v[124:125], s[34:35], v47, s30, v[2:3]
	s_add_i32 s35, s42, 20
	s_add_i32 s34, s19, 20
	v_or_b32_e32 v51, s35, v0
	v_or_b32_e32 v47, s34, v1
	v_add_u32_e32 v54, v51, v46
	v_add_u32_e32 v52, v47, v3
	v_ashrrev_i32_e32 v55, 31, v54
	v_ashrrev_i32_e32 v53, 31, v52
	v_lshlrev_b64 v[54:55], 12, v[54:55]
	v_lshlrev_b64 v[52:53], 12, v[52:53]
	v_lshl_add_u64 v[54:55], v[48:49], 0, v[54:55]
	v_lshl_add_u64 v[52:53], v[48:49], 0, v[52:53]
	global_load_dword v126, v[54:55], off
	global_load_dword v127, v[52:53], off
	v_mad_u64_u32 v[128:129], s[34:35], v51, s30, v[2:3]
	v_mad_u64_u32 v[130:131], s[34:35], v47, s30, v[2:3]
	s_add_i32 s35, s42, 24
	s_add_i32 s34, s19, 24
	v_or_b32_e32 v51, s35, v0
	v_or_b32_e32 v47, s34, v1
	s_add_i32 s42, s42, 28
	s_add_i32 s19, s19, 28
	s_cmp_lg_u32 s18, 0
	v_add_u32_e32 v54, v51, v46
	v_add_u32_e32 v52, v47, v3
	v_ashrrev_i32_e32 v55, 31, v54
	v_ashrrev_i32_e32 v53, 31, v52
	v_lshlrev_b64 v[54:55], 12, v[54:55]
	v_lshlrev_b64 v[52:53], 12, v[52:53]
	v_lshl_add_u64 v[54:55], v[48:49], 0, v[54:55]
	v_lshl_add_u64 v[52:53], v[48:49], 0, v[52:53]
	global_load_dword v132, v[54:55], off
	global_load_dword v133, v[52:53], off
	v_mad_u64_u32 v[134:135], s[34:35], v51, s30, v[2:3]
	v_mad_u64_u32 v[136:137], s[34:35], v47, s30, v[2:3]
	v_or_b32_e32 v51, s42, v0
	v_or_b32_e32 v47, s19, v1
	v_add_u32_e32 v54, v51, v46
	v_add_u32_e32 v52, v47, v3
	v_ashrrev_i32_e32 v55, 31, v54
	v_ashrrev_i32_e32 v53, 31, v52
	v_lshlrev_b64 v[54:55], 12, v[54:55]
	v_lshlrev_b64 v[52:53], 12, v[52:53]
	v_lshl_add_u64 v[54:55], v[48:49], 0, v[54:55]
	v_lshl_add_u64 v[52:53], v[48:49], 0, v[52:53]
	global_load_dword v138, v[54:55], off
	global_load_dword v139, v[52:53], off
	v_mad_u64_u32 v[140:141], s[34:35], v51, s30, v[2:3]
	v_mad_u64_u32 v[142:143], s[34:35], v47, s30, v[2:3]
	s_waitcnt vmcnt(0)
	ds_write_b32 v98, v96
	ds_write_b32 v100, v97
	ds_write_b32 v104, v102
	ds_write_b32 v106, v103
	ds_write_b32 v110, v108
	ds_write_b32 v112, v109
	ds_write_b32 v116, v114
	ds_write_b32 v118, v115
	ds_write_b32 v122, v120
	ds_write_b32 v124, v121
	ds_write_b32 v128, v126
	ds_write_b32 v130, v127
	ds_write_b32 v134, v132
	ds_write_b32 v136, v133
	ds_write_b32 v140, v138
	ds_write_b32 v142, v139
	s_cbranch_scc1 .LBB0_664
; #define LAS __attribute__((address_space(3)))
; __device__ __forceinline__ unsigned pk2(float lo, float hi) { const f32x2v v = {lo, hi}; return __builtin_bit_cast(unsigned, __builtin_convertvector(v, bf16x2_hw)); }
;     ...
;     for (int j = 0; j < 4; ++j) { const int n = (lane >> 3) + 8 * j; const LAS float* s = scr + (8 * c) * 33 + n;
;         u32x4v o; o.x = pk2(s[0 * 33], s[1 * 33]); o.y = pk2(s[2 * 33], s[3 * 33]); o.z = pk2(s[4 * 33], s[5 * 33]); o.w = pk2(s[6 * 33], s[7 * 33]);
;         *(u32x4v*)(WT + (size_t)(drow0 + n) * ldt + kdst + k0 + 8 * c) = o; }
;     asm volatile("s_waitcnt lgkmcnt(0)" ::: "memory");
	s_waitcnt lgkmcnt(0)
	ds_read2_b32 v[54:55], v68 offset0:33 offset1:41
	ds_read2_b32 v[56:57], v68 offset1:8
	ds_read2_b32 v[58:59], v68 offset0:66 offset1:74
	ds_read2_b32 v[60:61], v68 offset0:99 offset1:107
	ds_read2_b32 v[62:63], v68 offset0:132 offset1:140
	ds_read2_b32 v[64:65], v68 offset0:165 offset1:173
	ds_read2_b32 v[90:91], v68 offset0:198 offset1:206
	ds_read2_b32 v[92:93], v68 offset0:231 offset1:239
	v_or_b32_e32 v3, v50, v67
	v_mul_u32_u24_e32 v3, 0x500, v3
	v_mov_b32_e32 v47, v145
	v_lshlrev_b32_e32 v144, 1, v3
	v_or_b32_e32 v3, v50, v69
	v_lshl_add_u64 v[52:53], v[46:47], 1, v[14:15]
	v_mul_u32_u24_e32 v3, 0x500, v3
	s_waitcnt lgkmcnt(6)
	v_cvt_pk_bf16_f32 v46, v56, v54
	s_waitcnt lgkmcnt(4)
	v_cvt_pk_bf16_f32 v47, v58, v60
	s_waitcnt lgkmcnt(2)
	v_cvt_pk_bf16_f32 v48, v62, v64
	s_waitcnt lgkmcnt(0)
	v_cvt_pk_bf16_f32 v49, v90, v92
	v_lshl_add_u64 v[94:95], v[52:53], 0, v[144:145]
	v_lshlrev_b32_e32 v144, 1, v3
	global_store_dwordx4 v[94:95], v[46:49], off
	v_or_b32_e32 v3, v50, v70
	v_mul_u32_u24_e32 v3, 0x500, v3
	v_cvt_pk_bf16_f32 v46, v57, v55
	v_cvt_pk_bf16_f32 v47, v59, v61
	v_cvt_pk_bf16_f32 v48, v63, v65
	v_cvt_pk_bf16_f32 v49, v91, v93
	v_lshl_add_u64 v[54:55], v[52:53], 0, v[144:145]
	global_store_dwordx4 v[54:55], v[46:49], off
	ds_read2_b32 v[54:55], v68 offset0:16 offset1:24
	ds_read2_b32 v[56:57], v68 offset0:49 offset1:57
	ds_read2_b32 v[58:59], v68 offset0:82 offset1:90
	ds_read2_b32 v[60:61], v68 offset0:115 offset1:123
	ds_read2_b32 v[62:63], v68 offset0:148 offset1:156
	ds_read2_b32 v[64:65], v68 offset0:181 offset1:189
	ds_read2_b32 v[90:91], v68 offset0:214 offset1:222
	ds_read2_b32 v[92:93], v68 offset0:247 offset1:255
	v_lshlrev_b32_e32 v144, 1, v3
	v_or_b32_e32 v3, v50, v71
	v_mul_u32_u24_e32 v3, 0x500, v3
	s_waitcnt lgkmcnt(6)
	v_cvt_pk_bf16_f32 v46, v54, v56
	s_waitcnt lgkmcnt(4)
	v_cvt_pk_bf16_f32 v47, v58, v60
	s_waitcnt lgkmcnt(2)
	v_cvt_pk_bf16_f32 v48, v62, v64
	s_waitcnt lgkmcnt(0)
	v_cvt_pk_bf16_f32 v49, v90, v92
	v_lshl_add_u64 v[94:95], v[52:53], 0, v[144:145]
	v_lshlrev_b32_e32 v144, 1, v3
	global_store_dwordx4 v[94:95], v[46:49], off
	v_lshl_add_u64 v[50:51], v[52:53], 0, v[144:145]
	s_nop 0
	v_cvt_pk_bf16_f32 v46, v55, v57
	v_cvt_pk_bf16_f32 v47, v59, v61
	v_cvt_pk_bf16_f32 v48, v63, v65
	v_cvt_pk_bf16_f32 v49, v91, v93
	global_store_dwordx4 v[50:51], v[46:49], off
	s_waitcnt lgkmcnt(0)

;     ...
;     for (int i = 0; i < 32; ++i) { const int kk = 2 * i + (lane >> 5); float v = W[(size_t)(k0 + kk) * ldw + n0src + (lane & 31)]; if (gain) v *= gain[k0 + kk]; scr[kk * 33 + (lane & 31)] = v; }
; __device__ __forceinline__ void convert_weights(const Params& P, LAS unsigned char* lds, int gw, int NGW, int it0, int it1) {
;     ...
;         if (r < I_A) { const int kb = r / 32, nb = r % 32; transpose_item(P.in[18], DM, kb * 64, nb * 32, (bf16*)(ws + WS_WA), KMIX, nb * 32, nullptr, scr, lane, 0); continue; } r -= I_A;
;         if (r < I_B) { const int kb = r / 32, nb = r % 32; transpose_item(P.in[19], DM, kb * 64, nb * 32, (bf16*)(ws + WS_WA), KMIX, nb * 32, nullptr, scr, lane, 256); continue; } r -= I_B;
.LBB0_669:
	s_lshl_b32 s40, s15, 1
	s_lshl_b32 s19, s14, 1
	v_or_b32_e32 v51, s40, v0
	v_or_b32_e32 v47, s19, v1
	v_add_u32_e32 v54, v51, v46
	v_add_u32_e32 v52, v47, v3
	v_ashrrev_i32_e32 v55, 31, v54
	v_ashrrev_i32_e32 v53, 31, v52
	v_lshlrev_b64 v[54:55], 12, v[54:55]
	v_lshlrev_b64 v[52:53], 12, v[52:53]
	v_lshl_add_u64 v[54:55], v[48:49], 0, v[54:55]
	v_lshl_add_u64 v[52:53], v[48:49], 0, v[52:53]
	global_load_dword v96, v[54:55], off
	global_load_dword v97, v[52:53], off
	v_mad_u64_u32 v[98:99], s[34:35], v51, s30, v[2:3]
	v_mad_u64_u32 v[100:101], s[34:35], v47, s30, v[2:3]
	s_add_i32 s35, s40, 4
	s_add_i32 s34, s19, 4
	v_or_b32_e32 v51, s35, v0
	v_or_b32_e32 v47, s34, v1
	s_add_i32 s15, s15, 16
	s_add_i32 s14, s14, 16
	s_add_i32 s18, s18, -16
	v_add_u32_e32 v54, v51, v46
	v_add_u32_e32 v52, v47, v3
	v_ashrrev_i32_e32 v55, 31, v54
	v_ashrrev_i32_e32 v53, 31, v52
	v_lshlrev_b64 v[54:55], 12, v[54:55]
	v_lshlrev_b64 v[52:53], 12, v[52:53]
	v_lshl_add_u64 v[54:55], v[48:49], 0, v[54:55]
	v_lshl_add_u64 v[52:53], v[48:49], 0, v[52:53]
	global_load_dword v102, v[54:55], off
	global_load_dword v103, v[52:53], off
	v_mad_u64_u32 v[104:105], s[34:35], v51, s30, v[2:3]
	v_mad_u64_u32 v[106:107], s[34:35], v47, s30, v[2:3]
	s_add_i32 s35, s40, 8
	s_add_i32 s34, s19, 8
	v_or_b32_e32 v51, s35, v0
	v_or_b32_e32 v47, s34, v1
	v_add_u32_e32 v54, v51, v46
	v_add_u32_e32 v52, v47, v3
	v_ashrrev_i32_e32 v55, 31, v54
	v_ashrrev_i32_e32 v53, 31, v52
	v_lshlrev_b64 v[54:55], 12, v[54:55]
	v_lshlrev_b64 v[52:53], 12, v[52:53]
	v_lshl_add_u64 v[54:55], v[48:49], 0, v[54:55]
	v_lshl_add_u64 v[52:53], v[48:49], 0, v[52:53]
	global_load_dword v108, v[54:55], off
	global_load_dword v109, v[52:53], off
	v_mad_u64_u32 v[110:111], s[34:35], v51, s30, v[2:3]
	v_mad_u64_u32 v[112:113], s[34:35], v47, s30, v[2:3]
	s_add_i32 s35, s40, 12
	s_add_i32 s34, s19, 12
	v_or_b32_e32 v51, s35, v0
	v_or_b32_e32 v47, s34, v1
	v_add_u32_e32 v54, v51, v46
	v_add_u32_e32 v52, v47, v3
	v_ashrrev_i32_e32 v55, 31, v54
	v_ashrrev_i32_e32 v53, 31, v52
	v_lshlrev_b64 v[54:55], 12, v[54:55]
	v_lshlrev_b64 v[52:53], 12, v[52:53]
	v_lshl_add_u64 v[54:55], v[48:49], 0, v[54:55]
	v_lshl_add_u64 v[52:53], v[48:49], 0, v[52:53]
	global_load_dword v114, v[54:55], off
	global_load_dword v115, v[52:53], off
	v_mad_u64_u32 v[116:117], s[34:35], v51, s30, v[2:3]
	v_mad_u64_u32 v[118:119], s[34:35], v47, s30, v[2:3]
	s_add_i32 s35, s40, 16
	s_add_i32 s34, s19, 16
	v_or_b32_e32 v51, s35, v0
	v_or_b32_e32 v47, s34, v1
	v_add_u32_e32 v54, v51, v46
	v_add_u32_e32 v52, v47, v3
	v_ashrrev_i32_e32 v55, 31, v54
	v_ashrrev_i32_e32 v53, 31, v52
	v_lshlrev_b64 v[54:55], 12, v[54:55]
	v_lshlrev_b64 v[52:53], 12, v[52:53]
	v_lshl_add_u64 v[54:55], v[48:49], 0, v[54:55]
	v_lshl_add_u64 v[52:53], v[48:49], 0, v[52:53]
	global_load_dword v120, v[54:55], off
	global_load_dword v121, v[52:53], off
	v_mad_u64_u32 v[122:123], s[34:35], v51, s30, v[2:3]
	v_mad_u64_u32 v[124:125], s[34:35], v47, s30, v[2:3]
	s_add_i32 s35, s40, 20
	s_add_i32 s34, s19, 20
	v_or_b32_e32 v51, s35, v0
	v_or_b32_e32 v47, s34, v1
	v_add_u32_e32 v54, v51, v46
	v_add_u32_e32 v52, v47, v3
	v_ashrrev_i32_e32 v55, 31, v54
	v_ashrrev_i32_e32 v53, 31, v52
	v_lshlrev_b64 v[54:55], 12, v[54:55]
	v_lshlrev_b64 v[52:53], 12, v[52:53]
	v_lshl_add_u64 v[54:55], v[48:49], 0, v[54:55]
	v_lshl_add_u64 v[52:53], v[48:49], 0, v[52:53]
	global_load_dword v126, v[54:55], off
	global_load_dword v127, v[52:53], off
	v_mad_u64_u32 v[128:129], s[34:35], v51, s30, v[2:3]
	v_mad_u64_u32 v[130:131], s[34:35], v47, s30, v[2:3]
	s_add_i32 s35, s40, 24
	s_add_i32 s34, s19, 24
	v_or_b32_e32 v51, s35, v0
	v_or_b32_e32 v47, s34, v1
	s_add_i32 s40, s40, 28
	s_add_i32 s19, s19, 28
	s_cmp_lg_u32 s18, 0
	v_add_u32_e32 v54, v51, v46
	v_add_u32_e32 v52, v47, v3
	v_ashrrev_i32_e32 v55, 31, v54
	v_ashrrev_i32_e32 v53, 31, v52
	v_lshlrev_b64 v[54:55], 12, v[54:55]
	v_lshlrev_b64 v[52:53], 12, v[52:53]
	v_lshl_add_u64 v[54:55], v[48:49], 0, v[54:55]
	v_lshl_add_u64 v[52:53], v[48:49], 0, v[52:53]
	global_load_dword v132, v[54:55], off
	global_load_dword v133, v[52:53], off
	v_mad_u64_u32 v[134:135], s[34:35], v51, s30, v[2:3]
	v_mad_u64_u32 v[136:137], s[34:35], v47, s30, v[2:3]
	v_or_b32_e32 v51, s40, v0
	v_or_b32_e32 v47, s19, v1
	v_add_u32_e32 v54, v51, v46
	v_add_u32_e32 v52, v47, v3
	v_ashrrev_i32_e32 v55, 31, v54
	v_ashrrev_i32_e32 v53, 31, v52
	v_lshlrev_b64 v[54:55], 12, v[54:55]
	v_lshlrev_b64 v[52:53], 12, v[52:53]
	v_lshl_add_u64 v[54:55], v[48:49], 0, v[54:55]
	v_lshl_add_u64 v[52:53], v[48:49], 0, v[52:53]
	global_load_dword v138, v[54:55], off
	global_load_dword v139, v[52:53], off
	v_mad_u64_u32 v[140:141], s[34:35], v51, s30, v[2:3]
	v_mad_u64_u32 v[142:143], s[34:35], v47, s30, v[2:3]
	s_waitcnt vmcnt(0)
	ds_write_b32 v98, v96
	ds_write_b32 v100, v97
	ds_write_b32 v104, v102
	ds_write_b32 v106, v103
	ds_write_b32 v110, v108
	ds_write_b32 v112, v109
	ds_write_b32 v116, v114
	ds_write_b32 v118, v115
	ds_write_b32 v122, v120
	ds_write_b32 v124, v121
	ds_write_b32 v128, v126
	ds_write_b32 v130, v127
	ds_write_b32 v134, v132
	ds_write_b32 v136, v133
	ds_write_b32 v140, v138
	ds_write_b32 v142, v139
	s_cbranch_scc1 .LBB0_669
; #define LAS __attribute__((address_space(3)))
; __device__ __forceinline__ unsigned pk2(float lo, float hi) { const f32x2v v = {lo, hi}; return __builtin_bit_cast(unsigned, __builtin_convertvector(v, bf16x2_hw)); }
;     ...
;     for (int j = 0; j < 4; ++j) { const int n = (lane >> 3) + 8 * j; const LAS float* s = scr + (8 * c) * 33 + n;
;         u32x4v o; o.x = pk2(s[0 * 33], s[1 * 33]); o.y = pk2(s[2 * 33], s[3 * 33]); o.z = pk2(s[4 * 33], s[5 * 33]); o.w = pk2(s[6 * 33], s[7 * 33]);
;         *(u32x4v*)(WT + (size_t)(drow0 + n) * ldt + kdst + k0 + 8 * c) = o; }
;     asm volatile("s_waitcnt lgkmcnt(0)" ::: "memory");
	s_waitcnt lgkmcnt(0)
	ds_read2_b32 v[54:55], v68 offset0:33 offset1:41
	ds_read2_b32 v[56:57], v68 offset1:8
	ds_read2_b32 v[58:59], v68 offset0:66 offset1:74
	ds_read2_b32 v[60:61], v68 offset0:99 offset1:107
	ds_read2_b32 v[62:63], v68 offset0:132 offset1:140
	ds_read2_b32 v[64:65], v68 offset0:165 offset1:173
	ds_read2_b32 v[90:91], v68 offset0:198 offset1:206
	ds_read2_b32 v[92:93], v68 offset0:231 offset1:239
	v_or_b32_e32 v3, v50, v67
	v_mul_u32_u24_e32 v3, 0x500, v3
	v_mov_b32_e32 v47, v145
	v_lshlrev_b32_e32 v144, 1, v3
	v_or_b32_e32 v3, v50, v69
	v_lshl_add_u64 v[52:53], v[46:47], 1, v[16:17]
	v_mul_u32_u24_e32 v3, 0x500, v3
	s_waitcnt lgkmcnt(6)
	v_cvt_pk_bf16_f32 v46, v56, v54
	s_waitcnt lgkmcnt(4)
	v_cvt_pk_bf16_f32 v47, v58, v60
	s_waitcnt lgkmcnt(2)
	v_cvt_pk_bf16_f32 v48, v62, v64
	s_waitcnt lgkmcnt(0)
	v_cvt_pk_bf16_f32 v49, v90, v92
	v_lshl_add_u64 v[94:95], v[52:53], 0, v[144:145]
	v_lshlrev_b32_e32 v144, 1, v3
	global_store_dwordx4 v[94:95], v[46:49], off
	v_or_b32_e32 v3, v50, v70
	v_mul_u32_u24_e32 v3, 0x500, v3
	v_cvt_pk_bf16_f32 v46, v57, v55
	v_cvt_pk_bf16_f32 v47, v59, v61
	v_cvt_pk_bf16_f32 v48, v63, v65
	v_cvt_pk_bf16_f32 v49, v91, v93
	v_lshl_add_u64 v[54:55], v[52:53], 0, v[144:145]
	global_store_dwordx4 v[54:55], v[46:49], off
	ds_read2_b32 v[54:55], v68 offset0:16 offset1:24
	ds_read2_b32 v[56:57], v68 offset0:49 offset1:57
	ds_read2_b32 v[58:59], v68 offset0:82 offset1:90
	ds_read2_b32 v[60:61], v68 offset0:115 offset1:123
	ds_read2_b32 v[62:63], v68 offset0:148 offset1:156
	ds_read2_b32 v[64:65], v68 offset0:181 offset1:189
	ds_read2_b32 v[90:91], v68 offset0:214 offset1:222
	ds_read2_b32 v[92:93], v68 offset0:247 offset1:255
	v_lshlrev_b32_e32 v144, 1, v3
	v_or_b32_e32 v3, v50, v71
	v_mul_u32_u24_e32 v3, 0x500, v3
	s_waitcnt lgkmcnt(6)
	v_cvt_pk_bf16_f32 v46, v54, v56
	s_waitcnt lgkmcnt(4)
	v_cvt_pk_bf16_f32 v47, v58, v60
	s_waitcnt lgkmcnt(2)
	v_cvt_pk_bf16_f32 v48, v62, v64
	s_waitcnt lgkmcnt(0)
	v_cvt_pk_bf16_f32 v49, v90, v92
	v_lshl_add_u64 v[94:95], v[52:53], 0, v[144:145]
	v_lshlrev_b32_e32 v144, 1, v3
	global_store_dwordx4 v[94:95], v[46:49], off
	v_lshl_add_u64 v[50:51], v[52:53], 0, v[144:145]
	s_nop 0
	v_cvt_pk_bf16_f32 v46, v55, v57
	v_cvt_pk_bf16_f32 v47, v59, v61
	v_cvt_pk_bf16_f32 v48, v63, v65
	v_cvt_pk_bf16_f32 v49, v91, v93
	global_store_dwordx4 v[50:51], v[46:49], off
	s_waitcnt lgkmcnt(0)

; #pragma unroll 8
;     for (int i = 0; i < 32; ++i) { const int kk = 2 * i + (lane >> 5); float v = W[(size_t)(k0 + kk) * ldw + n0src + (lane & 31)]; if (gain) v *= gain[k0 + kk]; scr[kk * 33 + (lane & 31)] = v; }
;     asm volatile("s_waitcnt lgkmcnt(0)" ::: "memory");
.LBB0_675:
	v_lshl_add_u64 v[140:141], v[50:51], 0, s[18:19]
	global_load_dword v96, v[140:141], off
	v_lshl_add_u64 v[140:141], v[64:65], 0, s[18:19]
	global_load_dword v97, v[140:141], off
	v_lshl_add_u64 v[140:141], v[62:63], 0, s[18:19]
	global_load_dword v98, v[140:141], off
	v_lshl_add_u64 v[140:141], v[60:61], 0, s[18:19]
	global_load_dword v99, v[140:141], off
	v_lshl_add_u64 v[140:141], v[58:59], 0, s[18:19]
	global_load_dword v100, v[140:141], off
	v_lshl_add_u64 v[140:141], v[56:57], 0, s[18:19]
	global_load_dword v101, v[140:141], off
	v_lshl_add_u64 v[140:141], v[52:53], 0, s[18:19]
	global_load_dword v102, v[140:141], off
	v_lshl_add_u64 v[140:141], v[48:49], 0, s[18:19]
	global_load_dword v103, v[140:141], off
	s_add_u32 s18, s18, 0x84200
	s_addc_u32 s19, s19, 0
	v_lshl_add_u64 v[140:141], v[50:51], 0, s[18:19]
	global_load_dword v104, v[140:141], off
	v_lshl_add_u64 v[140:141], v[64:65], 0, s[18:19]
	global_load_dword v105, v[140:141], off
	v_lshl_add_u64 v[140:141], v[62:63], 0, s[18:19]
	global_load_dword v106, v[140:141], off
	v_lshl_add_u64 v[140:141], v[60:61], 0, s[18:19]
	global_load_dword v107, v[140:141], off
	v_lshl_add_u64 v[140:141], v[58:59], 0, s[18:19]
	global_load_dword v108, v[140:141], off
	v_lshl_add_u64 v[140:141], v[56:57], 0, s[18:19]
	global_load_dword v109, v[140:141], off
	v_lshl_add_u64 v[140:141], v[52:53], 0, s[18:19]
	global_load_dword v110, v[140:141], off
	v_lshl_add_u64 v[140:141], v[48:49], 0, s[18:19]
	global_load_dword v111, v[140:141], off
	s_add_u32 s18, s18, 0x84200
	s_addc_u32 s19, s19, 0
	v_lshl_add_u64 v[140:141], v[50:51], 0, s[18:19]
	global_load_dword v112, v[140:141], off
	v_lshl_add_u64 v[140:141], v[64:65], 0, s[18:19]
	global_load_dword v113, v[140:141], off
	v_lshl_add_u64 v[140:141], v[62:63], 0, s[18:19]
	global_load_dword v114, v[140:141], off
	v_lshl_add_u64 v[140:141], v[60:61], 0, s[18:19]
	global_load_dword v115, v[140:141], off
	v_lshl_add_u64 v[140:141], v[58:59], 0, s[18:19]
	global_load_dword v116, v[140:141], off
	v_lshl_add_u64 v[140:141], v[56:57], 0, s[18:19]
	global_load_dword v117, v[140:141], off
	v_lshl_add_u64 v[140:141], v[52:53], 0, s[18:19]
	global_load_dword v118, v[140:141], off
	v_lshl_add_u64 v[140:141], v[48:49], 0, s[18:19]
	global_load_dword v119, v[140:141], off
	s_add_u32 s18, s18, 0x84200
	s_addc_u32 s19, s19, 0
	v_lshl_add_u64 v[140:141], v[50:51], 0, s[18:19]
	global_load_dword v120, v[140:141], off
	v_lshl_add_u64 v[140:141], v[64:65], 0, s[18:19]
	global_load_dword v121, v[140:141], off
	v_lshl_add_u64 v[140:141], v[62:63], 0, s[18:19]
	global_load_dword v122, v[140:141], off
	v_lshl_add_u64 v[140:141], v[60:61], 0, s[18:19]
	global_load_dword v123, v[140:141], off
	v_lshl_add_u64 v[140:141], v[58:59], 0, s[18:19]
	global_load_dword v124, v[140:141], off
	v_lshl_add_u64 v[140:141], v[56:57], 0, s[18:19]
	global_load_dword v125, v[140:141], off
	v_lshl_add_u64 v[140:141], v[52:53], 0, s[18:19]
	global_load_dword v126, v[140:141], off
	v_lshl_add_u64 v[140:141], v[48:49], 0, s[18:19]
	global_load_dword v127, v[140:141], off
	s_andn2_b64 vcc, exec, s[16:17]
	s_cbranch_vccnz .Lcwg3_nogain
	global_load_dword v176, v[54:55], off offset:-56
	global_load_dword v177, v[54:55], off offset:-48
	global_load_dword v178, v[54:55], off offset:-40
	global_load_dword v179, v[54:55], off offset:-32
	global_load_dword v180, v[54:55], off offset:-24
	global_load_dword v181, v[54:55], off offset:-16
	global_load_dword v182, v[54:55], off offset:-8
	global_load_dword v183, v[54:55], off
	global_load_dword v184, v[54:55], off offset:8
	global_load_dword v185, v[54:55], off offset:16
	global_load_dword v186, v[54:55], off offset:24
	global_load_dword v187, v[54:55], off offset:32
	global_load_dword v188, v[54:55], off offset:40
	global_load_dword v189, v[54:55], off offset:48
	global_load_dword v190, v[54:55], off offset:56
	global_load_dword v191, v[54:55], off offset:64
	global_load_dword v192, v[54:55], off offset:72
	global_load_dword v193, v[54:55], off offset:80
	global_load_dword v194, v[54:55], off offset:88
	global_load_dword v195, v[54:55], off offset:96
	global_load_dword v196, v[54:55], off offset:104
	global_load_dword v197, v[54:55], off offset:112
	global_load_dword v198, v[54:55], off offset:120
	global_load_dword v199, v[54:55], off offset:128
	global_load_dword v200, v[54:55], off offset:136
	global_load_dword v201, v[54:55], off offset:144
	global_load_dword v202, v[54:55], off offset:152
	global_load_dword v203, v[54:55], off offset:160
	global_load_dword v204, v[54:55], off offset:168
	global_load_dword v205, v[54:55], off offset:176
	global_load_dword v206, v[54:55], off offset:184
	global_load_dword v207, v[54:55], off offset:192
	s_waitcnt vmcnt(0)
	v_mul_f32_e32 v96, v96, v176
	v_mul_f32_e32 v97, v97, v177
	v_mul_f32_e32 v98, v98, v178
	v_mul_f32_e32 v99, v99, v179
	v_mul_f32_e32 v100, v100, v180
	v_mul_f32_e32 v101, v101, v181
	v_mul_f32_e32 v102, v102, v182
	v_mul_f32_e32 v103, v103, v183
	v_mul_f32_e32 v104, v104, v184
	v_mul_f32_e32 v105, v105, v185
	v_mul_f32_e32 v106, v106, v186
	v_mul_f32_e32 v107, v107, v187
	v_mul_f32_e32 v108, v108, v188
	v_mul_f32_e32 v109, v109, v189
	v_mul_f32_e32 v110, v110, v190
	v_mul_f32_e32 v111, v111, v191
	v_mul_f32_e32 v112, v112, v192
	v_mul_f32_e32 v113, v113, v193
	v_mul_f32_e32 v114, v114, v194
	v_mul_f32_e32 v115, v115, v195
	v_mul_f32_e32 v116, v116, v196
	v_mul_f32_e32 v117, v117, v197
	v_mul_f32_e32 v118, v118, v198
	v_mul_f32_e32 v119, v119, v199
	v_mul_f32_e32 v120, v120, v200
	v_mul_f32_e32 v121, v121, v201
	v_mul_f32_e32 v122, v122, v202
	v_mul_f32_e32 v123, v123, v203
	v_mul_f32_e32 v124, v124, v204
	v_mul_f32_e32 v125, v125, v205
	v_mul_f32_e32 v126, v126, v206
	v_mul_f32_e32 v127, v127, v207
